# attention: static s_setprio 2 for waves 0-3 de-phases the two waves per SIMD; plus hand-written epi-0 epilogue, saddr DMA form, k-loop control hoist
# speedup vs baseline: 1.0416x; 1.0287x over previous
; __device__ __forceinline__ size_t a_base(const GDesc& d, const Unit& u, size_t tstepA) { return (size_t)u.pm * tstepA + (d.amode == 1 ? (size_t)u.pn * 512 : (size_t)0); }
; #define PG8_STAGE(bufoff, gbase, voff) do { _Pragma("unroll") for (int _i = 0; _i < 2; ++_i) \
;         __builtin_amdgcn_global_load_lds((const unsigned*)((const char*)(gbase) + (voff)[_i]), (LAS unsigned*)(lds + (bufoff) + ldsw + _i * 8192), 16, 0, 0); } while (0)
; #define PG8_WAIT_V(n) asm volatile("s_waitcnt vmcnt(" #n ")" ::: "memory")
; #define PG8_BAR __builtin_amdgcn_s_barrier()
; __device__ __forceinline__ void gemm_generic(LAS unsigned char* lds, const GDesc& d, int G, int bx) {
;     ...
;     for (int i = 0; i < 2; ++i) { int R, C; stage_rc(tid * 16 + i * 8192, R, C); const int Rb = (R & ~31) + perm32(R & 31);
;         voffA[i] = (unsigned)(R * d.lda + C) * 2u; voffB[i] = (unsigned)(Rb * d.ldb + C) * 2u; }
;     const size_t kstep = (size_t)(BK * 2);
;     const size_t hstepA = (size_t)HALF * d.lda * 2, hstepB = (size_t)HALF * d.ldb * 2, tstepB = 2 * hstepB, tstepA = 2 * hstepA;
;     const unsigned ldsw = (unsigned)wid * 1024u;
;     const int aoff = lds_byte(wr * 64 + fr, fq * 8), boff = lds_byte(wc * 32 + fr, fq * 8);
;     ...
;     Unit cur, nxt; int ui = 0;
;     if (!S.next(0, cur)) return;
;     f32x4 acc[2][2][4][2];
; #pragma unroll
;     for (int a = 0; a < 2; ++a)
; #pragma unroll
;         for (int b = 0; b < 2; ++b)
; #pragma unroll
;             for (int m = 0; m < 4; ++m)
; #pragma unroll
;                 for (int n = 0; n < 2; ++n) acc[a][b][m][n] = (f32x4){0.f, 0.f, 0.f, 0.f};
;     bf16x8 At[4][2], B0[2][2], B1[2][2];
;     const char* cA = d.A + a_base(d, cur, tstepA); const char* cB = d.Bt + (size_t)cur.pn * tstepB;
;     {
;         const char* cA1 = cA + a_koff(d, 1);
;         PG8_STAGE(PG8_SB(0, 0), cB, voffB); PG8_STAGE(PG8_SB(0, 1), cB + hstepB, voffB); PG8_STAGE(PG8_SA(0, 0), cA, voffA); PG8_STAGE(PG8_SA(0, 1), cA + hstepA, voffA);
;         if (wr == 1) PG8_BAR;
;         PG8_WAIT_V(2); PG8_BAR;
;         PG8_STAGE(PG8_SB(1, 0), cB + kstep, voffB); PG8_STAGE(PG8_SA(1, 0), cA1, voffA); PG8_STAGE(PG8_SB(1, 1), cB + hstepB + kstep, voffB);
;         PG8_WAIT_V(6); PG8_BAR;
.LBB0_242:
	s_add_i32 m0, s97, 0x18000
	v_lshl_add_u64 v[0:1], v[0:1], 0, s[20:21]
	s_waitcnt vmcnt(2)
	s_barrier
	global_load_lds_dwordx4 v[0:1], off
	v_lshl_add_u64 v[0:1], v[2:3], 0, s[20:21]
	s_add_i32 m0, s97, 0x1a000
	s_add_i32 s30, s97, 0x8000
	global_load_lds_dwordx4 v[0:1], off
	v_lshl_add_u64 v[0:1], v[8:9], 0, s[20:21]
	s_mov_b32 m0, s30
	s_add_i32 s31, s97, 0xa000
	global_load_lds_dwordx4 v[0:1], off
	v_lshl_add_u64 v[0:1], v[10:11], 0, s[20:21]
	s_mov_b32 m0, s31
	s_xor_b64 s[84:85], s[0:1], -1
	global_load_lds_dwordx4 v[0:1], off
	s_add_i32 m0, s97, 0x1c000
	v_lshl_add_u64 v[0:1], v[4:5], 0, s[20:21]
	global_load_lds_dwordx4 v[0:1], off
	v_lshl_add_u64 v[0:1], v[6:7], 0, s[20:21]
	s_add_i32 m0, s97, 0x1e000
	s_xor_b64 s[0:1], s[10:11], -1
	global_load_lds_dwordx4 v[0:1], off
	v_bfe_u32 v14, v12, 4, 2
	v_writelane_b32 v246, s0, 35
	v_and_b32_e32 v13, 15, v12
	v_lshlrev_b32_e32 v15, 4, v14
	v_lshlrev_b32_e32 v12, 2, v12
	v_writelane_b32 v246, s1, 36
	v_lshl_or_b32 v129, s12, 6, v13
	v_lshl_or_b32 v13, v13, 6, v15
	s_lshl_b32 s0, s12, 13
	v_and_b32_e32 v12, 32, v12
	v_bitop3_b32 v15, v13, s0, v12 bitop3:0xde
	s_lshl_b32 s0, s16, 5
	s_and_b32 s0, s0, 0x60
	s_lshl_b32 s1, s0, 7
	s_lshl_b32 s62, s13, 3
	s_add_i32 s63, s87, -2
	s_cmpk_lt_u32 s15, 0x100
	v_bitop3_b32 v231, v13, s1, v12 bitop3:0xde
	v_add_u32_e32 v250, 0x10000, v231
	v_add_u32_e32 v251, 0x14000, v231
	v_add_u32_e32 v252, 0x18000, v231
	v_add_u32_e32 v253, 0x1c000, v231
	s_cselect_b64 s[90:91], -1, 0
	v_lshl_or_b32 v206, v14, 3, s0
	s_add_u32 s92, s4, 0x8c80000
	v_readlane_b32 s0, v246, 27
	v_cvt_f32_u32_e32 v0, s62
	s_addc_u32 s93, s5, 0
	v_readlane_b32 s1, v246, 28
	s_cmp_lg_u64 s[0:1], 0
	s_cselect_b64 s[0:1], -1, 0
	v_writelane_b32 v246, s0, 37
	v_rcp_iflag_f32_e32 v0, v0
	s_waitcnt vmcnt(6)
	s_mov_b32 s69, s23
	v_writelane_b32 v246, s1, 38
	s_add_u32 s0, s4, 0x1d9a0000
	s_addc_u32 s1, s5, 0
	s_add_u32 s70, s4, 0x23b20000
	s_addc_u32 s71, s5, 0
	v_mul_f32_e32 v0, 0x4f7ffffe, v0
	s_cmp_eq_u64 s[56:57], 0
	v_cvt_u32_f32_e32 v0, v0
	v_writelane_b32 v246, s0, 39
	s_cselect_b64 s[72:73], -1, 0
	s_cmp_lg_u64 s[56:57], 0
	v_writelane_b32 v246, s1, 40
	s_cselect_b64 s[0:1], -1, 0
	v_writelane_b32 v246, s0, 19
	s_mov_b32 s52, 0
	v_cmp_eq_u32_e64 s[40:41], 0, v14
	v_writelane_b32 v246, s1, 20
	s_sub_i32 s0, 0, s62
	v_readfirstlane_b32 s1, v0
	s_mul_i32 s0, s0, s1
	s_mul_hi_u32 s0, s1, s0
	s_add_i32 s0, s1, s0
	v_add_u32_e32 v232, 0, v15
	s_barrier
	v_writelane_b32 v246, s0, 41
	s_branch .LBB0_245

; #define PG8_STAGE(bufoff, gbase, voff) do { _Pragma("unroll") for (int _i = 0; _i < 2; ++_i) \
;         __builtin_amdgcn_global_load_lds((const unsigned*)((const char*)(gbase) + (voff)[_i]), (LAS unsigned*)(lds + (bufoff) + ldsw + _i * 8192), 16, 0, 0); } while (0)
; #define PG8_LDA(dst, b, h) do { _Pragma("unroll") for (int m = 0; m < 4; ++m) _Pragma("unroll") for (int k = 0; k < 2; ++k) dst[m][k] = *(const LAS bf16x8*)(lds + PG8_SA(b, h) + aoff + m * 2048 + k * 1024); } while (0)
; #define PG8_LDB(dst, b, h) do { _Pragma("unroll") for (int n = 0; n < 2; ++n) _Pragma("unroll") for (int k = 0; k < 2; ++k) dst[n][k] = *(const LAS bf16x8*)(lds + PG8_SB(b, h) + boff + n * 2048 + k * 1024); } while (0)
; #define PG8_MMA(ai, bj, At, Bt) do { __builtin_amdgcn_s_setprio(1); _Pragma("unroll") for (int m = 0; m < 4; ++m) _Pragma("unroll") for (int n = 0; n < 2; ++n) _Pragma("unroll") for (int k = 0; k < 2; ++k) \
;         acc[ai][bj][m][n] = __builtin_amdgcn_mfma_f32_16x16x32_bf16(Bt[n][k], At[m][k], acc[ai][bj][m][n], 0, 0, 0); __builtin_amdgcn_s_setprio(0); } while (0)
; #define PG8_WAIT_V(n) asm volatile("s_waitcnt vmcnt(" #n ")" ::: "memory")
; #define PG8_WAIT_L(n) asm volatile("s_waitcnt lgkmcnt(" #n ")" ::: "memory")
; #define PG8_BAR __builtin_amdgcn_s_barrier()
; #define PG8_SCHED __builtin_amdgcn_sched_barrier(0)
; __device__ __forceinline__ void gemm_generic(LAS unsigned char* lds, const GDesc& d, int G, int bx) {
;     ...
;             PG8_LDB(B0, 0, 0); PG8_LDB(B1, 0, 1); PG8_SCHED; PG8_LDA(At, 0, 0); PG8_STAGE(PG8_SA(1, 1), a1 + hstepA, voffA);
;             PG8_WAIT_V(8); PG8_WAIT_L(0); PG8_BAR; PG8_MMA(0, 0, At, B0); PG8_MMA(0, 1, At, B1); PG8_BAR; PG8_SCHED;
;             PG8_LDA(At, 0, 1); PG8_STAGE(PG8_SB(0, 0), b2, voffB); PG8_STAGE(PG8_SB(0, 1), b2 + hstepB, voffB); PG8_STAGE(PG8_SA(0, 0), a2, voffA);
;             PG8_WAIT_V(8); PG8_WAIT_L(0); PG8_BAR; PG8_MMA(1, 0, At, B0); PG8_MMA(1, 1, At, B1); PG8_BAR; PG8_SCHED;
.Lg_body:
	ds_read_b128 v[130:133], v250
	ds_read_b128 v[134:137], v250 offset:1024
	ds_read_b128 v[138:141], v250 offset:2048
	ds_read_b128 v[142:145], v250 offset:3072
	ds_read_b128 v[146:149], v251
	ds_read_b128 v[150:153], v251 offset:1024
	ds_read_b128 v[154:157], v251 offset:2048
	ds_read_b128 v[158:161], v251 offset:3072
	s_add_u32 s34, s12, s34
	s_addc_u32 s35, s13, s35
	s_add_i32 m0, s97, 0xc000
	ds_read_b128 v[162:165], v232
	ds_read_b128 v[166:169], v232 offset:1024
	ds_read_b128 v[170:173], v232 offset:2048
	ds_read_b128 v[174:177], v232 offset:3072
	ds_read_b128 v[178:181], v232 offset:4096
	ds_read_b128 v[182:185], v232 offset:5120
	ds_read_b128 v[186:189], v232 offset:6144
	ds_read_b128 v[190:193], v232 offset:7168
	global_load_lds_dwordx4 v198, s[34:35]
	s_add_i32 m0, s97, 0xe000
	s_nop 0
	global_load_lds_dwordx4 v202, s[34:35]
	s_waitcnt vmcnt(8)
	s_waitcnt lgkmcnt(0)
	s_barrier
	s_setprio 1
	s_waitcnt lgkmcnt(0)
	v_mfma_f32_16x16x32_bf16 v[124:127], v[130:133], v[162:165], v[124:127]
	v_mfma_f32_16x16x32_bf16 v[120:123], v[138:141], v[162:165], v[120:123]
	v_mfma_f32_16x16x32_bf16 v[112:115], v[130:133], v[170:173], v[112:115]
	v_mfma_f32_16x16x32_bf16 v[104:107], v[138:141], v[170:173], v[104:107]
	v_mfma_f32_16x16x32_bf16 v[96:99], v[130:133], v[178:181], v[96:99]
	v_mfma_f32_16x16x32_bf16 v[88:91], v[138:141], v[178:181], v[88:91]
	v_mfma_f32_16x16x32_bf16 v[80:83], v[130:133], v[186:189], v[80:83]
	v_mfma_f32_16x16x32_bf16 v[72:75], v[138:141], v[186:189], v[72:75]
	v_mfma_f32_16x16x32_bf16 v[124:127], v[134:137], v[166:169], v[124:127]
	v_mfma_f32_16x16x32_bf16 v[120:123], v[142:145], v[166:169], v[120:123]
	v_mfma_f32_16x16x32_bf16 v[112:115], v[134:137], v[174:177], v[112:115]
	v_mfma_f32_16x16x32_bf16 v[104:107], v[142:145], v[174:177], v[104:107]
	v_mfma_f32_16x16x32_bf16 v[96:99], v[134:137], v[182:185], v[96:99]
	v_mfma_f32_16x16x32_bf16 v[88:91], v[142:145], v[182:185], v[88:91]
	v_mfma_f32_16x16x32_bf16 v[80:83], v[134:137], v[190:193], v[80:83]
	v_mfma_f32_16x16x32_bf16 v[72:75], v[142:145], v[190:193], v[72:75]
	s_setprio 0
	s_setprio 1
	v_mfma_f32_16x16x32_bf16 v[116:119], v[146:149], v[162:165], v[116:119]
	v_mfma_f32_16x16x32_bf16 v[108:111], v[154:157], v[162:165], v[108:111]
	v_mfma_f32_16x16x32_bf16 v[100:103], v[146:149], v[170:173], v[100:103]
	v_mfma_f32_16x16x32_bf16 v[92:95], v[154:157], v[170:173], v[92:95]
	v_mfma_f32_16x16x32_bf16 v[84:87], v[146:149], v[178:181], v[84:87]
	v_mfma_f32_16x16x32_bf16 v[76:79], v[154:157], v[178:181], v[76:79]
	v_mfma_f32_16x16x32_bf16 v[68:71], v[146:149], v[186:189], v[68:71]
	v_mfma_f32_16x16x32_bf16 v[64:67], v[154:157], v[186:189], v[64:67]
	v_mfma_f32_16x16x32_bf16 v[116:119], v[150:153], v[166:169], v[116:119]
	v_mfma_f32_16x16x32_bf16 v[108:111], v[158:161], v[166:169], v[108:111]
	v_mfma_f32_16x16x32_bf16 v[100:103], v[150:153], v[174:177], v[100:103]
	v_mfma_f32_16x16x32_bf16 v[92:95], v[158:161], v[174:177], v[92:95]
	v_mfma_f32_16x16x32_bf16 v[84:87], v[150:153], v[182:185], v[84:87]
	v_mfma_f32_16x16x32_bf16 v[76:79], v[158:161], v[182:185], v[76:79]
	v_mfma_f32_16x16x32_bf16 v[68:71], v[150:153], v[190:193], v[68:71]
	v_mfma_f32_16x16x32_bf16 v[64:67], v[158:161], v[190:193], v[64:67]
	s_setprio 0
	s_barrier
	s_add_i32 m0, s95, 0x10000
	ds_read_b128 v[162:165], v232 offset:16384
	ds_read_b128 v[166:169], v232 offset:17408
	ds_read_b128 v[170:173], v232 offset:18432
	ds_read_b128 v[174:177], v232 offset:19456
	ds_read_b128 v[178:181], v232 offset:20480
	ds_read_b128 v[182:185], v232 offset:21504
	ds_read_b128 v[186:189], v232 offset:22528
	ds_read_b128 v[190:193], v232 offset:23552
	global_load_lds_dwordx4 v200, s[44:45]
	s_add_i32 m0, s95, 0x12000
	s_add_u32 s34, s44, s76
	s_addc_u32 s35, s45, s77
	global_load_lds_dwordx4 v204, s[44:45]
	s_add_i32 m0, s95, 0x14000
	s_nop 0
	global_load_lds_dwordx4 v200, s[34:35]
	s_add_i32 m0, s95, 0x16000
	s_nop 0
	global_load_lds_dwordx4 v204, s[34:35]
	s_mov_b32 m0, s97
	s_nop 0
	global_load_lds_dwordx4 v198, s[28:29]
	s_mov_b32 m0, s27
	s_nop 0
	global_load_lds_dwordx4 v202, s[28:29]
	s_waitcnt vmcnt(8)
	s_waitcnt lgkmcnt(0)
	s_barrier
	s_setprio 1
	s_waitcnt lgkmcnt(0)
	v_mfma_f32_16x16x32_bf16 v[60:63], v[130:133], v[162:165], v[60:63]
	v_mfma_f32_16x16x32_bf16 v[56:59], v[138:141], v[162:165], v[56:59]
	v_mfma_f32_16x16x32_bf16 v[48:51], v[130:133], v[170:173], v[48:51]
	v_mfma_f32_16x16x32_bf16 v[40:43], v[138:141], v[170:173], v[40:43]
	v_mfma_f32_16x16x32_bf16 v[32:35], v[130:133], v[178:181], v[32:35]
	v_mfma_f32_16x16x32_bf16 v[24:27], v[138:141], v[178:181], v[24:27]
	v_mfma_f32_16x16x32_bf16 v[16:19], v[130:133], v[186:189], v[16:19]
	v_mfma_f32_16x16x32_bf16 v[8:11], v[138:141], v[186:189], v[8:11]
	v_mfma_f32_16x16x32_bf16 v[60:63], v[134:137], v[166:169], v[60:63]
	v_mfma_f32_16x16x32_bf16 v[56:59], v[142:145], v[166:169], v[56:59]
	v_mfma_f32_16x16x32_bf16 v[48:51], v[134:137], v[174:177], v[48:51]
	v_mfma_f32_16x16x32_bf16 v[40:43], v[142:145], v[174:177], v[40:43]
	v_mfma_f32_16x16x32_bf16 v[32:35], v[134:137], v[182:185], v[32:35]
	v_mfma_f32_16x16x32_bf16 v[24:27], v[142:145], v[182:185], v[24:27]
	v_mfma_f32_16x16x32_bf16 v[16:19], v[134:137], v[190:193], v[16:19]
	v_mfma_f32_16x16x32_bf16 v[8:11], v[142:145], v[190:193], v[8:11]
	s_setprio 0
	s_setprio 1
	v_mfma_f32_16x16x32_bf16 v[52:55], v[146:149], v[162:165], v[52:55]
	v_mfma_f32_16x16x32_bf16 v[44:47], v[154:157], v[162:165], v[44:47]
	v_mfma_f32_16x16x32_bf16 v[36:39], v[146:149], v[170:173], v[36:39]
	v_mfma_f32_16x16x32_bf16 v[28:31], v[154:157], v[170:173], v[28:31]
	v_mfma_f32_16x16x32_bf16 v[20:23], v[146:149], v[178:181], v[20:23]
	v_mfma_f32_16x16x32_bf16 v[12:15], v[154:157], v[178:181], v[12:15]
	v_mfma_f32_16x16x32_bf16 v[4:7], v[146:149], v[186:189], v[4:7]
	v_mfma_f32_16x16x32_bf16 v[0:3], v[154:157], v[186:189], v[0:3]
	v_mfma_f32_16x16x32_bf16 v[52:55], v[150:153], v[166:169], v[52:55]
	v_mfma_f32_16x16x32_bf16 v[44:47], v[158:161], v[166:169], v[44:47]
	v_mfma_f32_16x16x32_bf16 v[36:39], v[150:153], v[174:177], v[36:39]
	v_mfma_f32_16x16x32_bf16 v[28:31], v[158:161], v[174:177], v[28:31]
	v_mfma_f32_16x16x32_bf16 v[20:23], v[150:153], v[182:185], v[20:23]
	v_mfma_f32_16x16x32_bf16 v[12:15], v[158:161], v[182:185], v[12:15]
	v_mfma_f32_16x16x32_bf16 v[4:7], v[150:153], v[190:193], v[4:7]
	v_mfma_f32_16x16x32_bf16 v[0:3], v[158:161], v[190:193], v[0:3]
	s_setprio 0
	s_barrier
; #define PG8_STAGE(bufoff, gbase, voff) do { _Pragma("unroll") for (int _i = 0; _i < 2; ++_i) \
;         __builtin_amdgcn_global_load_lds((const unsigned*)((const char*)(gbase) + (voff)[_i]), (LAS unsigned*)(lds + (bufoff) + ldsw + _i * 8192), 16, 0, 0); } while (0)
; #define PG8_LDA(dst, b, h) do { _Pragma("unroll") for (int m = 0; m < 4; ++m) _Pragma("unroll") for (int k = 0; k < 2; ++k) dst[m][k] = *(const LAS bf16x8*)(lds + PG8_SA(b, h) + aoff + m * 2048 + k * 1024); } while (0)
; #define PG8_LDB(dst, b, h) do { _Pragma("unroll") for (int n = 0; n < 2; ++n) _Pragma("unroll") for (int k = 0; k < 2; ++k) dst[n][k] = *(const LAS bf16x8*)(lds + PG8_SB(b, h) + boff + n * 2048 + k * 1024); } while (0)
; #define PG8_MMA(ai, bj, At, Bt) do { __builtin_amdgcn_s_setprio(1); _Pragma("unroll") for (int m = 0; m < 4; ++m) _Pragma("unroll") for (int n = 0; n < 2; ++n) _Pragma("unroll") for (int k = 0; k < 2; ++k) \
;         acc[ai][bj][m][n] = __builtin_amdgcn_mfma_f32_16x16x32_bf16(Bt[n][k], At[m][k], acc[ai][bj][m][n], 0, 0, 0); __builtin_amdgcn_s_setprio(0); } while (0)
; #define PG8_WAIT_V(n) asm volatile("s_waitcnt vmcnt(" #n ")" ::: "memory")
; #define PG8_WAIT_L(n) asm volatile("s_waitcnt lgkmcnt(" #n ")" ::: "memory")
; #define PG8_BAR __builtin_amdgcn_s_barrier()
; #define PG8_SCHED __builtin_amdgcn_sched_barrier(0)
; __device__ __forceinline__ void gemm_generic(LAS unsigned char* lds, const GDesc& d, int G, int bx) {
;     ...
;         for (int t = 0; t < nt; t += 2) {
;             const bool last = (t == nt - 2);
;             const char* a1 = cA + a_koff(d, t + 1);
;             const char* a2 = last ? nA : cA + a_koff(d, t + 2); const char* b2 = last ? nB : cB + (size_t)(t + 2) * kstep;
;             const char* a3 = last ? nA + a_koff(d, 1) : cA + a_koff(d, t + 3); const char* b3 = b2 + kstep;
;     ...
;             PG8_LDB(B0, 1, 0); PG8_LDB(B1, 1, 1); PG8_SCHED; PG8_LDA(At, 1, 0); PG8_STAGE(PG8_SA(0, 1), a2 + hstepA, voffA);
;             PG8_WAIT_V(8); PG8_WAIT_L(0); PG8_BAR; PG8_MMA(0, 0, At, B0); PG8_MMA(0, 1, At, B1); PG8_BAR; PG8_SCHED;
;             PG8_LDA(At, 1, 1); PG8_STAGE(PG8_SB(1, 0), b3, voffB); PG8_STAGE(PG8_SB(1, 1), b3 + hstepB, voffB); PG8_STAGE(PG8_SA(1, 0), a3, voffA);
;             PG8_WAIT_V(8); PG8_WAIT_L(0); PG8_BAR; PG8_MMA(1, 0, At, B0); PG8_MMA(1, 1, At, B1); PG8_BAR; PG8_SCHED;
	s_add_i32 s26, 0, 0x1c000
	ds_read_b128 v[130:133], v252
	ds_read_b128 v[134:137], v252 offset:1024
	ds_read_b128 v[138:141], v252 offset:2048
	ds_read_b128 v[142:145], v252 offset:3072
	ds_read_b128 v[146:149], v253
	ds_read_b128 v[150:153], v253 offset:1024
	ds_read_b128 v[154:157], v253 offset:2048
	ds_read_b128 v[158:161], v253 offset:3072
	s_add_u32 s28, s28, s74
	s_addc_u32 s29, s29, s75
	s_mov_b32 m0, s64
	ds_read_b128 v[162:165], v232 offset:32768
	ds_read_b128 v[166:169], v232 offset:33792
	ds_read_b128 v[170:173], v232 offset:34816
	ds_read_b128 v[174:177], v232 offset:35840
	ds_read_b128 v[178:181], v232 offset:36864
	ds_read_b128 v[182:185], v232 offset:37888
	ds_read_b128 v[186:189], v232 offset:38912
	ds_read_b128 v[190:193], v232 offset:39936
	global_load_lds_dwordx4 v198, s[28:29]
	s_mov_b32 m0, s65
	s_nop 0
	global_load_lds_dwordx4 v202, s[28:29]
	s_waitcnt vmcnt(8)
	s_waitcnt lgkmcnt(0)
	s_barrier
	s_setprio 1
	s_waitcnt lgkmcnt(0)
	v_mfma_f32_16x16x32_bf16 v[124:127], v[130:133], v[162:165], v[124:127]
	v_mfma_f32_16x16x32_bf16 v[120:123], v[138:141], v[162:165], v[120:123]
	v_mfma_f32_16x16x32_bf16 v[112:115], v[130:133], v[170:173], v[112:115]
	v_mfma_f32_16x16x32_bf16 v[104:107], v[138:141], v[170:173], v[104:107]
	v_mfma_f32_16x16x32_bf16 v[96:99], v[130:133], v[178:181], v[96:99]
	v_mfma_f32_16x16x32_bf16 v[88:91], v[138:141], v[178:181], v[88:91]
	v_mfma_f32_16x16x32_bf16 v[80:83], v[130:133], v[186:189], v[80:83]
	v_mfma_f32_16x16x32_bf16 v[72:75], v[138:141], v[186:189], v[72:75]
	v_mfma_f32_16x16x32_bf16 v[124:127], v[134:137], v[166:169], v[124:127]
	v_mfma_f32_16x16x32_bf16 v[120:123], v[142:145], v[166:169], v[120:123]
	v_mfma_f32_16x16x32_bf16 v[112:115], v[134:137], v[174:177], v[112:115]
	v_mfma_f32_16x16x32_bf16 v[104:107], v[142:145], v[174:177], v[104:107]
	v_mfma_f32_16x16x32_bf16 v[96:99], v[134:137], v[182:185], v[96:99]
	v_mfma_f32_16x16x32_bf16 v[88:91], v[142:145], v[182:185], v[88:91]
	v_mfma_f32_16x16x32_bf16 v[80:83], v[134:137], v[190:193], v[80:83]
	v_mfma_f32_16x16x32_bf16 v[72:75], v[142:145], v[190:193], v[72:75]
	s_setprio 0
	s_setprio 1
	v_mfma_f32_16x16x32_bf16 v[116:119], v[146:149], v[162:165], v[116:119]
	v_mfma_f32_16x16x32_bf16 v[108:111], v[154:157], v[162:165], v[108:111]
	v_mfma_f32_16x16x32_bf16 v[100:103], v[146:149], v[170:173], v[100:103]
	v_mfma_f32_16x16x32_bf16 v[92:95], v[154:157], v[170:173], v[92:95]
	v_mfma_f32_16x16x32_bf16 v[84:87], v[146:149], v[178:181], v[84:87]
	v_mfma_f32_16x16x32_bf16 v[76:79], v[154:157], v[178:181], v[76:79]
	v_mfma_f32_16x16x32_bf16 v[68:71], v[146:149], v[186:189], v[68:71]
	v_mfma_f32_16x16x32_bf16 v[64:67], v[154:157], v[186:189], v[64:67]
	v_mfma_f32_16x16x32_bf16 v[116:119], v[150:153], v[166:169], v[116:119]
	v_mfma_f32_16x16x32_bf16 v[108:111], v[158:161], v[166:169], v[108:111]
	v_mfma_f32_16x16x32_bf16 v[100:103], v[150:153], v[174:177], v[100:103]
	v_mfma_f32_16x16x32_bf16 v[92:95], v[158:161], v[174:177], v[92:95]
	v_mfma_f32_16x16x32_bf16 v[84:87], v[150:153], v[182:185], v[84:87]
	v_mfma_f32_16x16x32_bf16 v[76:79], v[158:161], v[182:185], v[76:79]
	v_mfma_f32_16x16x32_bf16 v[68:71], v[150:153], v[190:193], v[68:71]
	v_mfma_f32_16x16x32_bf16 v[64:67], v[158:161], v[190:193], v[64:67]
	s_setprio 0
	s_barrier
	s_add_u32 s46, s44, s20
	s_addc_u32 s47, s45, s21
	s_add_i32 m0, s95, 0x18000
	ds_read_b128 v[162:165], v232 offset:49152
	ds_read_b128 v[166:169], v232 offset:50176
	ds_read_b128 v[170:173], v232 offset:51200
	ds_read_b128 v[174:177], v232 offset:52224
	ds_read_b128 v[178:181], v232 offset:53248
	ds_read_b128 v[182:185], v232 offset:54272
	ds_read_b128 v[186:189], v232 offset:55296
	ds_read_b128 v[190:193], v232 offset:56320
	global_load_lds_dwordx4 v200, s[46:47]
	s_add_i32 m0, s95, 0x1a000
	s_nop 0
	global_load_lds_dwordx4 v204, s[46:47]
	s_add_u32 s46, s34, s20
	s_addc_u32 s47, s35, s21
	s_add_i32 m0, s95, 0x1c000
	s_nop 0
	global_load_lds_dwordx4 v200, s[46:47]
	s_add_i32 m0, s95, 0x1e000
	s_nop 0
	global_load_lds_dwordx4 v204, s[46:47]
	s_mov_b32 m0, s30
	s_nop 0
	global_load_lds_dwordx4 v198, s[24:25]
	s_mov_b32 m0, s31
	s_nop 0
	global_load_lds_dwordx4 v202, s[24:25]
	s_add_u32 s10, s10, 0x180
	s_addc_u32 s11, s11, 0
	s_add_u32 s15, s15, 0x100
	s_addc_u32 s16, s16, 0
	s_mov_b32 s17, s22
	s_cmp_ge_u32 s22, s87
	s_cbranch_scc1 .Lg_ctl_done
	s_or_b32 s22, s17, 1
	s_lshl_b64 s[34:35], s[22:23], 7
	s_add_i32 s22, s17, 2
	s_lshl_b64 s[28:29], s[22:23], 7
	s_add_i32 s24, s17, 3
	s_mov_b32 s25, s23
	s_lshl_b64 s[24:25], s[24:25], 7
	s_and_b64 vcc, exec, s[84:85]
	s_cbranch_scc1 .Lg_ctl_std
	s_add_u32 s34, s10, 0xfffffe80
	s_addc_u32 s35, s11, -1
	s_add_u32 s28, s10, 0xffffff80
	s_addc_u32 s29, s11, -1
	s_mov_b64 s[24:25], s[10:11]

; __device__ __forceinline__ unsigned cvt_pk_bf16(float lo, float hi) { unsigned r; asm volatile("v_cvt_pk_bf16_f32 %0, %1, %2" : "=v"(r) : "v"(lo), "v"(hi)); return r; }
; __device__ __forceinline__ void run_epi(const GDesc& d, const f32x4 (&acc)[2][2][4][2], const Unit& u, int wr, int wc, int fr, int fq) {
;     ...
;     if (epi == 0) {
;         float rsv[2][4];
; #pragma unroll
;         for (int ai = 0; ai < 2; ++ai)
; #pragma unroll
;             for (int m = 0; m < 4; ++m) rsv[ai][m] = d.ss ? d.ss[row0 + ai * HALF + m * 16] : 0.f;
; #pragma unroll
;         for (int ai = 0; ai < 2; ++ai)
; #pragma unroll
;             for (int m = 0; m < 4; ++m) {
;                 const int row = row0 + ai * HALF + m * 16;
;                 const float rs = d.ss ? __builtin_amdgcn_rsqf(rsv[ai][m] * (1.0f / DM) + EPS) : 1.f;
; #pragma unroll
;                 for (int bj = 0; bj < 2; ++bj) {
;                     const f32x4 v0 = acc[ai][bj][m][0], v1 = acc[ai][bj][m][1];
;                     float v[8] = {v0[0], v0[1], v0[2], v0[3], v1[0], v1[1], v1[2], v1[3]};
; #pragma unroll
;                     for (int i = 0; i < 8; ++i) { float x = v[i] * rs;
;                         if (d.act == 1) x = __builtin_amdgcn_rcpf(1.f + __builtin_amdgcn_exp2f(-1.4426950408889634f * x));
;                         else if (d.act == 2) { x = fmaxf(x, 0.f); x = x * x; }
;                         v[i] = x; }
;                     u32x4 w; w.x = cvt_pk_bf16(v[0], v[1]); w.y = cvt_pk_bf16(v[2], v[3]); w.z = cvt_pk_bf16(v[4], v[5]); w.w = cvt_pk_bf16(v[6], v[7]);
;                     *(u32x4*)(d.O + (size_t)row * d.ldc + col0 + bj * HALF) = w;
.LBB0_403:
	s_andn2_b64 vcc, exec, s[0:1]
	s_cbranch_vccnz .LBB0_1450
	s_cmp_lg_u32 s94, 1
	s_mov_b64 s[0:1], -1
	s_cbranch_scc0 .LBB0_1448
	s_waitcnt lgkmcnt(0)
	v_mul_lo_u32 v140, v208, s58
	v_mov_b32_e32 v132, 1.0
	v_mov_b32_e32 v133, 1.0
	v_mov_b32_e32 v134, 1.0
	v_mov_b32_e32 v135, 1.0
	v_mov_b32_e32 v136, 1.0
	v_mov_b32_e32 v137, 1.0
	v_mov_b32_e32 v138, 1.0
	v_mov_b32_e32 v139, 1.0
	s_and_b64 vcc, exec, s[72:73]
	s_cbranch_vccnz .Le0_rs_done
	v_lshlrev_b32_e32 v141, 2, v208
	global_load_dword v132, v141, s[56:57]
	global_load_dword v133, v141, s[56:57] offset:64
	global_load_dword v134, v141, s[56:57] offset:128
	global_load_dword v135, v141, s[56:57] offset:192
	global_load_dword v136, v141, s[56:57] offset:512
	global_load_dword v137, v141, s[56:57] offset:576
	global_load_dword v138, v141, s[56:57] offset:640
	global_load_dword v139, v141, s[56:57] offset:704
	s_waitcnt vmcnt(0)
	v_fmamk_f32 v132, v132, 0x3a000000, v225
	v_fmamk_f32 v133, v133, 0x3a000000, v225
	v_fmamk_f32 v134, v134, 0x3a000000, v225
	v_fmamk_f32 v135, v135, 0x3a000000, v225
	v_fmamk_f32 v136, v136, 0x3a000000, v225
	v_fmamk_f32 v137, v137, 0x3a000000, v225
	v_fmamk_f32 v138, v138, 0x3a000000, v225
	v_fmamk_f32 v139, v139, 0x3a000000, v225
	v_rsq_f32_e32 v132, v132
	v_rsq_f32_e32 v133, v133
	v_rsq_f32_e32 v134, v134
	v_rsq_f32_e32 v135, v135
	v_rsq_f32_e32 v136, v136
	v_rsq_f32_e32 v137, v137
	v_rsq_f32_e32 v138, v138
	v_rsq_f32_e32 v139, v139
.Le0_rs_done:
	v_add_u32_e32 v140, v140, v210
	s_lshl_b32 s8, s58, 5
	s_lshl_b32 s9, s58, 8
	v_lshlrev_b32_e32 v140, 1, v140
	s_cmp_eq_u32 s86, 1
	v_add_u32_e32 v141, s8, v140
	v_add_u32_e32 v144, s9, v140
	v_add_u32_e32 v142, s8, v141
	v_add_u32_e32 v145, s8, v144
	v_add_u32_e32 v143, s8, v142
	v_add_u32_e32 v146, s8, v145
	v_add_u32_e32 v147, s8, v146
	s_cbranch_scc1 .Le0_sigmoid
	s_cmp_eq_u32 s86, 2
	s_cbranch_scc1 .Le0_relu2
	v_mul_f32_e32 v124, v124, v132
	v_mul_f32_e32 v125, v125, v132
	v_mul_f32_e32 v126, v126, v132
	v_mul_f32_e32 v127, v127, v132
	v_mul_f32_e32 v120, v120, v132
	v_mul_f32_e32 v121, v121, v132
	v_mul_f32_e32 v122, v122, v132
	v_mul_f32_e32 v123, v123, v132
	v_cvt_pk_bf16_f32 v124, v124, v125
	v_cvt_pk_bf16_f32 v125, v126, v127
	v_cvt_pk_bf16_f32 v126, v120, v121
	v_cvt_pk_bf16_f32 v127, v122, v123
	global_store_dwordx4 v140, v[124:127], s[54:55]
	v_mul_f32_e32 v116, v116, v132
	v_mul_f32_e32 v117, v117, v132
	v_mul_f32_e32 v118, v118, v132
	v_mul_f32_e32 v119, v119, v132
	v_mul_f32_e32 v108, v108, v132
	v_mul_f32_e32 v109, v109, v132
	v_mul_f32_e32 v110, v110, v132
	v_mul_f32_e32 v111, v111, v132
	v_cvt_pk_bf16_f32 v116, v116, v117
	v_cvt_pk_bf16_f32 v117, v118, v119
	v_cvt_pk_bf16_f32 v118, v108, v109
	v_cvt_pk_bf16_f32 v119, v110, v111
	global_store_dwordx4 v140, v[116:119], s[54:55] offset:256
	v_mul_f32_e32 v112, v112, v133
	v_mul_f32_e32 v113, v113, v133
	v_mul_f32_e32 v114, v114, v133
	v_mul_f32_e32 v115, v115, v133
	v_mul_f32_e32 v104, v104, v133
	v_mul_f32_e32 v105, v105, v133
	v_mul_f32_e32 v106, v106, v133
	v_mul_f32_e32 v107, v107, v133
	v_cvt_pk_bf16_f32 v112, v112, v113
	v_cvt_pk_bf16_f32 v113, v114, v115
	v_cvt_pk_bf16_f32 v114, v104, v105
	v_cvt_pk_bf16_f32 v115, v106, v107
	global_store_dwordx4 v141, v[112:115], s[54:55]
	v_mul_f32_e32 v100, v100, v133
	v_mul_f32_e32 v101, v101, v133
	v_mul_f32_e32 v102, v102, v133
	v_mul_f32_e32 v103, v103, v133
	v_mul_f32_e32 v92, v92, v133
	v_mul_f32_e32 v93, v93, v133
	v_mul_f32_e32 v94, v94, v133
	v_mul_f32_e32 v95, v95, v133
	v_cvt_pk_bf16_f32 v100, v100, v101
	v_cvt_pk_bf16_f32 v101, v102, v103
	v_cvt_pk_bf16_f32 v102, v92, v93
	v_cvt_pk_bf16_f32 v103, v94, v95
	global_store_dwordx4 v141, v[100:103], s[54:55] offset:256
	v_mul_f32_e32 v96, v96, v134
	v_mul_f32_e32 v97, v97, v134
	v_mul_f32_e32 v98, v98, v134
	v_mul_f32_e32 v99, v99, v134
	v_mul_f32_e32 v88, v88, v134
	v_mul_f32_e32 v89, v89, v134
	v_mul_f32_e32 v90, v90, v134
	v_mul_f32_e32 v91, v91, v134
	v_cvt_pk_bf16_f32 v96, v96, v97
	v_cvt_pk_bf16_f32 v97, v98, v99
	v_cvt_pk_bf16_f32 v98, v88, v89
	v_cvt_pk_bf16_f32 v99, v90, v91
	global_store_dwordx4 v142, v[96:99], s[54:55]
	v_mul_f32_e32 v84, v84, v134
	v_mul_f32_e32 v85, v85, v134
	v_mul_f32_e32 v86, v86, v134
	v_mul_f32_e32 v87, v87, v134
	v_mul_f32_e32 v76, v76, v134
	v_mul_f32_e32 v77, v77, v134
	v_mul_f32_e32 v78, v78, v134
	v_mul_f32_e32 v79, v79, v134
	v_cvt_pk_bf16_f32 v84, v84, v85
	v_cvt_pk_bf16_f32 v85, v86, v87
	v_cvt_pk_bf16_f32 v86, v76, v77
	v_cvt_pk_bf16_f32 v87, v78, v79
	global_store_dwordx4 v142, v[84:87], s[54:55] offset:256
	v_mul_f32_e32 v80, v80, v135
	v_mul_f32_e32 v81, v81, v135
	v_mul_f32_e32 v82, v82, v135
	v_mul_f32_e32 v83, v83, v135
	v_mul_f32_e32 v72, v72, v135
	v_mul_f32_e32 v73, v73, v135
	v_mul_f32_e32 v74, v74, v135
	v_mul_f32_e32 v75, v75, v135
	v_cvt_pk_bf16_f32 v80, v80, v81
	v_cvt_pk_bf16_f32 v81, v82, v83
	v_cvt_pk_bf16_f32 v82, v72, v73
	v_cvt_pk_bf16_f32 v83, v74, v75
	global_store_dwordx4 v143, v[80:83], s[54:55]
	v_mul_f32_e32 v68, v68, v135
	v_mul_f32_e32 v69, v69, v135
	v_mul_f32_e32 v70, v70, v135
	v_mul_f32_e32 v71, v71, v135
	v_mul_f32_e32 v64, v64, v135
	v_mul_f32_e32 v65, v65, v135
	v_mul_f32_e32 v66, v66, v135
	v_mul_f32_e32 v67, v67, v135
	v_cvt_pk_bf16_f32 v68, v68, v69
	v_cvt_pk_bf16_f32 v69, v70, v71
	v_cvt_pk_bf16_f32 v70, v64, v65
	v_cvt_pk_bf16_f32 v71, v66, v67
	global_store_dwordx4 v143, v[68:71], s[54:55] offset:256
	v_mul_f32_e32 v60, v60, v136
	v_mul_f32_e32 v61, v61, v136
	v_mul_f32_e32 v62, v62, v136
	v_mul_f32_e32 v63, v63, v136
	v_mul_f32_e32 v56, v56, v136
	v_mul_f32_e32 v57, v57, v136
	v_mul_f32_e32 v58, v58, v136
	v_mul_f32_e32 v59, v59, v136
	v_cvt_pk_bf16_f32 v60, v60, v61
; __device__ __forceinline__ unsigned cvt_pk_bf16(float lo, float hi) { unsigned r; asm volatile("v_cvt_pk_bf16_f32 %0, %1, %2" : "=v"(r) : "v"(lo), "v"(hi)); return r; }
; __device__ __forceinline__ void run_epi(const GDesc& d, const f32x4 (&acc)[2][2][4][2], const Unit& u, int wr, int wc, int fr, int fq) {
;     ...
; #pragma unroll
;                 for (int bj = 0; bj < 2; ++bj) {
;                     const f32x4 v0 = acc[ai][bj][m][0], v1 = acc[ai][bj][m][1];
;                     float v[8] = {v0[0], v0[1], v0[2], v0[3], v1[0], v1[1], v1[2], v1[3]};
; #pragma unroll
;                     for (int i = 0; i < 8; ++i) { float x = v[i] * rs;
;                         if (d.act == 1) x = __builtin_amdgcn_rcpf(1.f + __builtin_amdgcn_exp2f(-1.4426950408889634f * x));
;                         else if (d.act == 2) { x = fmaxf(x, 0.f); x = x * x; }
;                         v[i] = x; }
;                     u32x4 w; w.x = cvt_pk_bf16(v[0], v[1]); w.y = cvt_pk_bf16(v[2], v[3]); w.z = cvt_pk_bf16(v[4], v[5]); w.w = cvt_pk_bf16(v[6], v[7]);
;                     *(u32x4*)(d.O + (size_t)row * d.ldc + col0 + bj * HALF) = w;
	v_cvt_pk_bf16_f32 v61, v62, v63
	v_cvt_pk_bf16_f32 v62, v56, v57
	v_cvt_pk_bf16_f32 v63, v58, v59
	global_store_dwordx4 v144, v[60:63], s[54:55]
	v_mul_f32_e32 v52, v52, v136
	v_mul_f32_e32 v53, v53, v136
	v_mul_f32_e32 v54, v54, v136
	v_mul_f32_e32 v55, v55, v136
	v_mul_f32_e32 v44, v44, v136
	v_mul_f32_e32 v45, v45, v136
	v_mul_f32_e32 v46, v46, v136
	v_mul_f32_e32 v47, v47, v136
	v_cvt_pk_bf16_f32 v52, v52, v53
	v_cvt_pk_bf16_f32 v53, v54, v55
	v_cvt_pk_bf16_f32 v54, v44, v45
	v_cvt_pk_bf16_f32 v55, v46, v47
	global_store_dwordx4 v144, v[52:55], s[54:55] offset:256
	v_mul_f32_e32 v48, v48, v137
	v_mul_f32_e32 v49, v49, v137
	v_mul_f32_e32 v50, v50, v137
	v_mul_f32_e32 v51, v51, v137
	v_mul_f32_e32 v40, v40, v137
	v_mul_f32_e32 v41, v41, v137
	v_mul_f32_e32 v42, v42, v137
	v_mul_f32_e32 v43, v43, v137
	v_cvt_pk_bf16_f32 v48, v48, v49
	v_cvt_pk_bf16_f32 v49, v50, v51
	v_cvt_pk_bf16_f32 v50, v40, v41
	v_cvt_pk_bf16_f32 v51, v42, v43
	global_store_dwordx4 v145, v[48:51], s[54:55]
	v_mul_f32_e32 v36, v36, v137
	v_mul_f32_e32 v37, v37, v137
	v_mul_f32_e32 v38, v38, v137
	v_mul_f32_e32 v39, v39, v137
	v_mul_f32_e32 v28, v28, v137
	v_mul_f32_e32 v29, v29, v137
	v_mul_f32_e32 v30, v30, v137
	v_mul_f32_e32 v31, v31, v137
	v_cvt_pk_bf16_f32 v36, v36, v37
	v_cvt_pk_bf16_f32 v37, v38, v39
	v_cvt_pk_bf16_f32 v38, v28, v29
	v_cvt_pk_bf16_f32 v39, v30, v31
	global_store_dwordx4 v145, v[36:39], s[54:55] offset:256
	v_mul_f32_e32 v32, v32, v138
	v_mul_f32_e32 v33, v33, v138
	v_mul_f32_e32 v34, v34, v138
	v_mul_f32_e32 v35, v35, v138
	v_mul_f32_e32 v24, v24, v138
	v_mul_f32_e32 v25, v25, v138
	v_mul_f32_e32 v26, v26, v138
	v_mul_f32_e32 v27, v27, v138
	v_cvt_pk_bf16_f32 v32, v32, v33
	v_cvt_pk_bf16_f32 v33, v34, v35
	v_cvt_pk_bf16_f32 v34, v24, v25
	v_cvt_pk_bf16_f32 v35, v26, v27
	global_store_dwordx4 v146, v[32:35], s[54:55]
	v_mul_f32_e32 v20, v20, v138
	v_mul_f32_e32 v21, v21, v138
	v_mul_f32_e32 v22, v22, v138
	v_mul_f32_e32 v23, v23, v138
	v_mul_f32_e32 v12, v12, v138
	v_mul_f32_e32 v13, v13, v138
	v_mul_f32_e32 v14, v14, v138
	v_mul_f32_e32 v15, v15, v138
	v_cvt_pk_bf16_f32 v20, v20, v21
	v_cvt_pk_bf16_f32 v21, v22, v23
	v_cvt_pk_bf16_f32 v22, v12, v13
	v_cvt_pk_bf16_f32 v23, v14, v15
	global_store_dwordx4 v146, v[20:23], s[54:55] offset:256
	v_mul_f32_e32 v16, v16, v139
	v_mul_f32_e32 v17, v17, v139
	v_mul_f32_e32 v18, v18, v139
	v_mul_f32_e32 v19, v19, v139
	v_mul_f32_e32 v8, v8, v139
	v_mul_f32_e32 v9, v9, v139
	v_mul_f32_e32 v10, v10, v139
	v_mul_f32_e32 v11, v11, v139
	v_cvt_pk_bf16_f32 v16, v16, v17
	v_cvt_pk_bf16_f32 v17, v18, v19
	v_cvt_pk_bf16_f32 v18, v8, v9
	v_cvt_pk_bf16_f32 v19, v10, v11
	global_store_dwordx4 v147, v[16:19], s[54:55]
	v_mul_f32_e32 v4, v4, v139
	v_mul_f32_e32 v5, v5, v139
	v_mul_f32_e32 v6, v6, v139
	v_mul_f32_e32 v7, v7, v139
	v_mul_f32_e32 v0, v0, v139
	v_mul_f32_e32 v1, v1, v139
	v_mul_f32_e32 v2, v2, v139
	v_mul_f32_e32 v3, v3, v139
	v_cvt_pk_bf16_f32 v4, v4, v5
	v_cvt_pk_bf16_f32 v5, v6, v7
	v_cvt_pk_bf16_f32 v6, v0, v1
	v_cvt_pk_bf16_f32 v7, v2, v3
	global_store_dwordx4 v147, v[4:7], s[54:55] offset:256
	s_branch .Le0_done
.Le0_sigmoid:
	v_mul_f32_e32 v124, v124, v132
	v_mul_f32_e32 v125, v125, v132
	v_mul_f32_e32 v126, v126, v132
	v_mul_f32_e32 v127, v127, v132
	v_mul_f32_e32 v120, v120, v132
	v_mul_f32_e32 v121, v121, v132
	v_mul_f32_e32 v122, v122, v132
	v_mul_f32_e32 v123, v123, v132
	v_mul_f32_e32 v124, 0xbfb8aa3b, v124
	v_mul_f32_e32 v125, 0xbfb8aa3b, v125
	v_mul_f32_e32 v126, 0xbfb8aa3b, v126
	v_mul_f32_e32 v127, 0xbfb8aa3b, v127
	v_mul_f32_e32 v120, 0xbfb8aa3b, v120
	v_mul_f32_e32 v121, 0xbfb8aa3b, v121
	v_mul_f32_e32 v122, 0xbfb8aa3b, v122
	v_mul_f32_e32 v123, 0xbfb8aa3b, v123
	v_exp_f32_e32 v124, v124
	v_exp_f32_e32 v125, v125
	v_exp_f32_e32 v126, v126
	v_exp_f32_e32 v127, v127
	v_exp_f32_e32 v120, v120
	v_exp_f32_e32 v121, v121
	v_exp_f32_e32 v122, v122
	v_exp_f32_e32 v123, v123
	v_add_f32_e32 v124, 1.0, v124
	v_add_f32_e32 v125, 1.0, v125
	v_add_f32_e32 v126, 1.0, v126
	v_add_f32_e32 v127, 1.0, v127
	v_add_f32_e32 v120, 1.0, v120
	v_add_f32_e32 v121, 1.0, v121
	v_add_f32_e32 v122, 1.0, v122
	v_add_f32_e32 v123, 1.0, v123
	v_rcp_f32_e32 v124, v124
	v_rcp_f32_e32 v125, v125
	v_rcp_f32_e32 v126, v126
	v_rcp_f32_e32 v127, v127
	v_rcp_f32_e32 v120, v120
	v_rcp_f32_e32 v121, v121
	v_rcp_f32_e32 v122, v122
	v_rcp_f32_e32 v123, v123
	v_cvt_pk_bf16_f32 v124, v124, v125
	v_cvt_pk_bf16_f32 v125, v126, v127
	v_cvt_pk_bf16_f32 v126, v120, v121
	v_cvt_pk_bf16_f32 v127, v122, v123
	global_store_dwordx4 v140, v[124:127], s[54:55]
	v_mul_f32_e32 v116, v116, v132
	v_mul_f32_e32 v117, v117, v132
	v_mul_f32_e32 v118, v118, v132
	v_mul_f32_e32 v119, v119, v132
	v_mul_f32_e32 v108, v108, v132
	v_mul_f32_e32 v109, v109, v132
	v_mul_f32_e32 v110, v110, v132
	v_mul_f32_e32 v111, v111, v132
	v_mul_f32_e32 v116, 0xbfb8aa3b, v116
	v_mul_f32_e32 v117, 0xbfb8aa3b, v117
	v_mul_f32_e32 v118, 0xbfb8aa3b, v118
	v_mul_f32_e32 v119, 0xbfb8aa3b, v119
	v_mul_f32_e32 v108, 0xbfb8aa3b, v108
	v_mul_f32_e32 v109, 0xbfb8aa3b, v109
	v_mul_f32_e32 v110, 0xbfb8aa3b, v110
	v_mul_f32_e32 v111, 0xbfb8aa3b, v111
	v_exp_f32_e32 v116, v116
	v_exp_f32_e32 v117, v117
	v_exp_f32_e32 v118, v118
	v_exp_f32_e32 v119, v119
	v_exp_f32_e32 v108, v108
	v_exp_f32_e32 v109, v109
	v_exp_f32_e32 v110, v110
	v_exp_f32_e32 v111, v111
	v_add_f32_e32 v116, 1.0, v116
	v_add_f32_e32 v117, 1.0, v117
	v_add_f32_e32 v118, 1.0, v118
	v_add_f32_e32 v119, 1.0, v119
	v_add_f32_e32 v108, 1.0, v108
	v_add_f32_e32 v109, 1.0, v109
	v_add_f32_e32 v110, 1.0, v110
	v_add_f32_e32 v111, 1.0, v111
	v_rcp_f32_e32 v116, v116
	v_rcp_f32_e32 v117, v117
	v_rcp_f32_e32 v118, v118
; __device__ __forceinline__ unsigned cvt_pk_bf16(float lo, float hi) { unsigned r; asm volatile("v_cvt_pk_bf16_f32 %0, %1, %2" : "=v"(r) : "v"(lo), "v"(hi)); return r; }
; __device__ __forceinline__ void run_epi(const GDesc& d, const f32x4 (&acc)[2][2][4][2], const Unit& u, int wr, int wc, int fr, int fq) {
;     ...
; #pragma unroll
;                 for (int bj = 0; bj < 2; ++bj) {
;                     const f32x4 v0 = acc[ai][bj][m][0], v1 = acc[ai][bj][m][1];
;                     float v[8] = {v0[0], v0[1], v0[2], v0[3], v1[0], v1[1], v1[2], v1[3]};
; #pragma unroll
;                     for (int i = 0; i < 8; ++i) { float x = v[i] * rs;
;                         if (d.act == 1) x = __builtin_amdgcn_rcpf(1.f + __builtin_amdgcn_exp2f(-1.4426950408889634f * x));
;                         else if (d.act == 2) { x = fmaxf(x, 0.f); x = x * x; }
;                         v[i] = x; }
;                     u32x4 w; w.x = cvt_pk_bf16(v[0], v[1]); w.y = cvt_pk_bf16(v[2], v[3]); w.z = cvt_pk_bf16(v[4], v[5]); w.w = cvt_pk_bf16(v[6], v[7]);
;                     *(u32x4*)(d.O + (size_t)row * d.ldc + col0 + bj * HALF) = w;
	v_rcp_f32_e32 v119, v119
	v_rcp_f32_e32 v108, v108
	v_rcp_f32_e32 v109, v109
	v_rcp_f32_e32 v110, v110
	v_rcp_f32_e32 v111, v111
	v_cvt_pk_bf16_f32 v116, v116, v117
	v_cvt_pk_bf16_f32 v117, v118, v119
	v_cvt_pk_bf16_f32 v118, v108, v109
	v_cvt_pk_bf16_f32 v119, v110, v111
	global_store_dwordx4 v140, v[116:119], s[54:55] offset:256
	v_mul_f32_e32 v112, v112, v133
	v_mul_f32_e32 v113, v113, v133
	v_mul_f32_e32 v114, v114, v133
	v_mul_f32_e32 v115, v115, v133
	v_mul_f32_e32 v104, v104, v133
	v_mul_f32_e32 v105, v105, v133
	v_mul_f32_e32 v106, v106, v133
	v_mul_f32_e32 v107, v107, v133
	v_mul_f32_e32 v112, 0xbfb8aa3b, v112
	v_mul_f32_e32 v113, 0xbfb8aa3b, v113
	v_mul_f32_e32 v114, 0xbfb8aa3b, v114
	v_mul_f32_e32 v115, 0xbfb8aa3b, v115
	v_mul_f32_e32 v104, 0xbfb8aa3b, v104
	v_mul_f32_e32 v105, 0xbfb8aa3b, v105
	v_mul_f32_e32 v106, 0xbfb8aa3b, v106
	v_mul_f32_e32 v107, 0xbfb8aa3b, v107
	v_exp_f32_e32 v112, v112
	v_exp_f32_e32 v113, v113
	v_exp_f32_e32 v114, v114
	v_exp_f32_e32 v115, v115
	v_exp_f32_e32 v104, v104
	v_exp_f32_e32 v105, v105
	v_exp_f32_e32 v106, v106
	v_exp_f32_e32 v107, v107
	v_add_f32_e32 v112, 1.0, v112
	v_add_f32_e32 v113, 1.0, v113
	v_add_f32_e32 v114, 1.0, v114
	v_add_f32_e32 v115, 1.0, v115
	v_add_f32_e32 v104, 1.0, v104
	v_add_f32_e32 v105, 1.0, v105
	v_add_f32_e32 v106, 1.0, v106
	v_add_f32_e32 v107, 1.0, v107
	v_rcp_f32_e32 v112, v112
	v_rcp_f32_e32 v113, v113
	v_rcp_f32_e32 v114, v114
	v_rcp_f32_e32 v115, v115
	v_rcp_f32_e32 v104, v104
	v_rcp_f32_e32 v105, v105
	v_rcp_f32_e32 v106, v106
	v_rcp_f32_e32 v107, v107
	v_cvt_pk_bf16_f32 v112, v112, v113
	v_cvt_pk_bf16_f32 v113, v114, v115
	v_cvt_pk_bf16_f32 v114, v104, v105
	v_cvt_pk_bf16_f32 v115, v106, v107
	global_store_dwordx4 v141, v[112:115], s[54:55]
	v_mul_f32_e32 v100, v100, v133
	v_mul_f32_e32 v101, v101, v133
	v_mul_f32_e32 v102, v102, v133
	v_mul_f32_e32 v103, v103, v133
	v_mul_f32_e32 v92, v92, v133
	v_mul_f32_e32 v93, v93, v133
	v_mul_f32_e32 v94, v94, v133
	v_mul_f32_e32 v95, v95, v133
	v_mul_f32_e32 v100, 0xbfb8aa3b, v100
	v_mul_f32_e32 v101, 0xbfb8aa3b, v101
	v_mul_f32_e32 v102, 0xbfb8aa3b, v102
	v_mul_f32_e32 v103, 0xbfb8aa3b, v103
	v_mul_f32_e32 v92, 0xbfb8aa3b, v92
	v_mul_f32_e32 v93, 0xbfb8aa3b, v93
	v_mul_f32_e32 v94, 0xbfb8aa3b, v94
	v_mul_f32_e32 v95, 0xbfb8aa3b, v95
	v_exp_f32_e32 v100, v100
	v_exp_f32_e32 v101, v101
	v_exp_f32_e32 v102, v102
	v_exp_f32_e32 v103, v103
	v_exp_f32_e32 v92, v92
	v_exp_f32_e32 v93, v93
	v_exp_f32_e32 v94, v94
	v_exp_f32_e32 v95, v95
	v_add_f32_e32 v100, 1.0, v100
	v_add_f32_e32 v101, 1.0, v101
	v_add_f32_e32 v102, 1.0, v102
	v_add_f32_e32 v103, 1.0, v103
	v_add_f32_e32 v92, 1.0, v92
	v_add_f32_e32 v93, 1.0, v93
	v_add_f32_e32 v94, 1.0, v94
	v_add_f32_e32 v95, 1.0, v95
	v_rcp_f32_e32 v100, v100
	v_rcp_f32_e32 v101, v101
	v_rcp_f32_e32 v102, v102
	v_rcp_f32_e32 v103, v103
	v_rcp_f32_e32 v92, v92
	v_rcp_f32_e32 v93, v93
	v_rcp_f32_e32 v94, v94
	v_rcp_f32_e32 v95, v95
	v_cvt_pk_bf16_f32 v100, v100, v101
	v_cvt_pk_bf16_f32 v101, v102, v103
	v_cvt_pk_bf16_f32 v102, v92, v93
	v_cvt_pk_bf16_f32 v103, v94, v95
	global_store_dwordx4 v141, v[100:103], s[54:55] offset:256
	v_mul_f32_e32 v96, v96, v134
	v_mul_f32_e32 v97, v97, v134
	v_mul_f32_e32 v98, v98, v134
	v_mul_f32_e32 v99, v99, v134
	v_mul_f32_e32 v88, v88, v134
	v_mul_f32_e32 v89, v89, v134
	v_mul_f32_e32 v90, v90, v134
	v_mul_f32_e32 v91, v91, v134
	v_mul_f32_e32 v96, 0xbfb8aa3b, v96
	v_mul_f32_e32 v97, 0xbfb8aa3b, v97
	v_mul_f32_e32 v98, 0xbfb8aa3b, v98
	v_mul_f32_e32 v99, 0xbfb8aa3b, v99
	v_mul_f32_e32 v88, 0xbfb8aa3b, v88
	v_mul_f32_e32 v89, 0xbfb8aa3b, v89
	v_mul_f32_e32 v90, 0xbfb8aa3b, v90
	v_mul_f32_e32 v91, 0xbfb8aa3b, v91
	v_exp_f32_e32 v96, v96
	v_exp_f32_e32 v97, v97
	v_exp_f32_e32 v98, v98
	v_exp_f32_e32 v99, v99
	v_exp_f32_e32 v88, v88
	v_exp_f32_e32 v89, v89
	v_exp_f32_e32 v90, v90
	v_exp_f32_e32 v91, v91
	v_add_f32_e32 v96, 1.0, v96
	v_add_f32_e32 v97, 1.0, v97
	v_add_f32_e32 v98, 1.0, v98
	v_add_f32_e32 v99, 1.0, v99
	v_add_f32_e32 v88, 1.0, v88
	v_add_f32_e32 v89, 1.0, v89
	v_add_f32_e32 v90, 1.0, v90
	v_add_f32_e32 v91, 1.0, v91
	v_rcp_f32_e32 v96, v96
	v_rcp_f32_e32 v97, v97
	v_rcp_f32_e32 v98, v98
	v_rcp_f32_e32 v99, v99
	v_rcp_f32_e32 v88, v88
	v_rcp_f32_e32 v89, v89
	v_rcp_f32_e32 v90, v90
	v_rcp_f32_e32 v91, v91
	v_cvt_pk_bf16_f32 v96, v96, v97
	v_cvt_pk_bf16_f32 v97, v98, v99
	v_cvt_pk_bf16_f32 v98, v88, v89
	v_cvt_pk_bf16_f32 v99, v90, v91
	global_store_dwordx4 v142, v[96:99], s[54:55]
	v_mul_f32_e32 v84, v84, v134
	v_mul_f32_e32 v85, v85, v134
	v_mul_f32_e32 v86, v86, v134
	v_mul_f32_e32 v87, v87, v134
	v_mul_f32_e32 v76, v76, v134
	v_mul_f32_e32 v77, v77, v134
	v_mul_f32_e32 v78, v78, v134
	v_mul_f32_e32 v79, v79, v134
	v_mul_f32_e32 v84, 0xbfb8aa3b, v84
	v_mul_f32_e32 v85, 0xbfb8aa3b, v85
	v_mul_f32_e32 v86, 0xbfb8aa3b, v86
	v_mul_f32_e32 v87, 0xbfb8aa3b, v87
	v_mul_f32_e32 v76, 0xbfb8aa3b, v76
	v_mul_f32_e32 v77, 0xbfb8aa3b, v77
	v_mul_f32_e32 v78, 0xbfb8aa3b, v78
	v_mul_f32_e32 v79, 0xbfb8aa3b, v79
	v_exp_f32_e32 v84, v84
	v_exp_f32_e32 v85, v85
	v_exp_f32_e32 v86, v86
	v_exp_f32_e32 v87, v87
	v_exp_f32_e32 v76, v76
	v_exp_f32_e32 v77, v77
	v_exp_f32_e32 v78, v78
	v_exp_f32_e32 v79, v79
	v_add_f32_e32 v84, 1.0, v84
	v_add_f32_e32 v85, 1.0, v85
	v_add_f32_e32 v86, 1.0, v86
	v_add_f32_e32 v87, 1.0, v87
	v_add_f32_e32 v76, 1.0, v76
	v_add_f32_e32 v77, 1.0, v77
	v_add_f32_e32 v78, 1.0, v78
	v_add_f32_e32 v79, 1.0, v79
	v_rcp_f32_e32 v84, v84
	v_rcp_f32_e32 v85, v85
	v_rcp_f32_e32 v86, v86
	v_rcp_f32_e32 v87, v87
	v_rcp_f32_e32 v76, v76
	v_rcp_f32_e32 v77, v77
	v_rcp_f32_e32 v78, v78
	v_rcp_f32_e32 v79, v79
	v_cvt_pk_bf16_f32 v84, v84, v85
; __device__ __forceinline__ unsigned cvt_pk_bf16(float lo, float hi) { unsigned r; asm volatile("v_cvt_pk_bf16_f32 %0, %1, %2" : "=v"(r) : "v"(lo), "v"(hi)); return r; }
; __device__ __forceinline__ void run_epi(const GDesc& d, const f32x4 (&acc)[2][2][4][2], const Unit& u, int wr, int wc, int fr, int fq) {
;     ...
; #pragma unroll
;                 for (int bj = 0; bj < 2; ++bj) {
;                     const f32x4 v0 = acc[ai][bj][m][0], v1 = acc[ai][bj][m][1];
;                     float v[8] = {v0[0], v0[1], v0[2], v0[3], v1[0], v1[1], v1[2], v1[3]};
; #pragma unroll
;                     for (int i = 0; i < 8; ++i) { float x = v[i] * rs;
;                         if (d.act == 1) x = __builtin_amdgcn_rcpf(1.f + __builtin_amdgcn_exp2f(-1.4426950408889634f * x));
;                         else if (d.act == 2) { x = fmaxf(x, 0.f); x = x * x; }
;                         v[i] = x; }
;                     u32x4 w; w.x = cvt_pk_bf16(v[0], v[1]); w.y = cvt_pk_bf16(v[2], v[3]); w.z = cvt_pk_bf16(v[4], v[5]); w.w = cvt_pk_bf16(v[6], v[7]);
;                     *(u32x4*)(d.O + (size_t)row * d.ldc + col0 + bj * HALF) = w;
	v_cvt_pk_bf16_f32 v85, v86, v87
	v_cvt_pk_bf16_f32 v86, v76, v77
	v_cvt_pk_bf16_f32 v87, v78, v79
	global_store_dwordx4 v142, v[84:87], s[54:55] offset:256
	v_mul_f32_e32 v80, v80, v135
	v_mul_f32_e32 v81, v81, v135
	v_mul_f32_e32 v82, v82, v135
	v_mul_f32_e32 v83, v83, v135
	v_mul_f32_e32 v72, v72, v135
	v_mul_f32_e32 v73, v73, v135
	v_mul_f32_e32 v74, v74, v135
	v_mul_f32_e32 v75, v75, v135
	v_mul_f32_e32 v80, 0xbfb8aa3b, v80
	v_mul_f32_e32 v81, 0xbfb8aa3b, v81
	v_mul_f32_e32 v82, 0xbfb8aa3b, v82
	v_mul_f32_e32 v83, 0xbfb8aa3b, v83
	v_mul_f32_e32 v72, 0xbfb8aa3b, v72
	v_mul_f32_e32 v73, 0xbfb8aa3b, v73
	v_mul_f32_e32 v74, 0xbfb8aa3b, v74
	v_mul_f32_e32 v75, 0xbfb8aa3b, v75
	v_exp_f32_e32 v80, v80
	v_exp_f32_e32 v81, v81
	v_exp_f32_e32 v82, v82
	v_exp_f32_e32 v83, v83
	v_exp_f32_e32 v72, v72
	v_exp_f32_e32 v73, v73
	v_exp_f32_e32 v74, v74
	v_exp_f32_e32 v75, v75
	v_add_f32_e32 v80, 1.0, v80
	v_add_f32_e32 v81, 1.0, v81
	v_add_f32_e32 v82, 1.0, v82
	v_add_f32_e32 v83, 1.0, v83
	v_add_f32_e32 v72, 1.0, v72
	v_add_f32_e32 v73, 1.0, v73
	v_add_f32_e32 v74, 1.0, v74
	v_add_f32_e32 v75, 1.0, v75
	v_rcp_f32_e32 v80, v80
	v_rcp_f32_e32 v81, v81
	v_rcp_f32_e32 v82, v82
	v_rcp_f32_e32 v83, v83
	v_rcp_f32_e32 v72, v72
	v_rcp_f32_e32 v73, v73
	v_rcp_f32_e32 v74, v74
	v_rcp_f32_e32 v75, v75
	v_cvt_pk_bf16_f32 v80, v80, v81
	v_cvt_pk_bf16_f32 v81, v82, v83
	v_cvt_pk_bf16_f32 v82, v72, v73
	v_cvt_pk_bf16_f32 v83, v74, v75
	global_store_dwordx4 v143, v[80:83], s[54:55]
	v_mul_f32_e32 v68, v68, v135
	v_mul_f32_e32 v69, v69, v135
	v_mul_f32_e32 v70, v70, v135
	v_mul_f32_e32 v71, v71, v135
	v_mul_f32_e32 v64, v64, v135
	v_mul_f32_e32 v65, v65, v135
	v_mul_f32_e32 v66, v66, v135
	v_mul_f32_e32 v67, v67, v135
	v_mul_f32_e32 v68, 0xbfb8aa3b, v68
	v_mul_f32_e32 v69, 0xbfb8aa3b, v69
	v_mul_f32_e32 v70, 0xbfb8aa3b, v70
	v_mul_f32_e32 v71, 0xbfb8aa3b, v71
	v_mul_f32_e32 v64, 0xbfb8aa3b, v64
	v_mul_f32_e32 v65, 0xbfb8aa3b, v65
	v_mul_f32_e32 v66, 0xbfb8aa3b, v66
	v_mul_f32_e32 v67, 0xbfb8aa3b, v67
	v_exp_f32_e32 v68, v68
	v_exp_f32_e32 v69, v69
	v_exp_f32_e32 v70, v70
	v_exp_f32_e32 v71, v71
	v_exp_f32_e32 v64, v64
	v_exp_f32_e32 v65, v65
	v_exp_f32_e32 v66, v66
	v_exp_f32_e32 v67, v67
	v_add_f32_e32 v68, 1.0, v68
	v_add_f32_e32 v69, 1.0, v69
	v_add_f32_e32 v70, 1.0, v70
	v_add_f32_e32 v71, 1.0, v71
	v_add_f32_e32 v64, 1.0, v64
	v_add_f32_e32 v65, 1.0, v65
	v_add_f32_e32 v66, 1.0, v66
	v_add_f32_e32 v67, 1.0, v67
	v_rcp_f32_e32 v68, v68
	v_rcp_f32_e32 v69, v69
	v_rcp_f32_e32 v70, v70
	v_rcp_f32_e32 v71, v71
	v_rcp_f32_e32 v64, v64
	v_rcp_f32_e32 v65, v65
	v_rcp_f32_e32 v66, v66
	v_rcp_f32_e32 v67, v67
	v_cvt_pk_bf16_f32 v68, v68, v69
	v_cvt_pk_bf16_f32 v69, v70, v71
	v_cvt_pk_bf16_f32 v70, v64, v65
	v_cvt_pk_bf16_f32 v71, v66, v67
	global_store_dwordx4 v143, v[68:71], s[54:55] offset:256
	v_mul_f32_e32 v60, v60, v136
	v_mul_f32_e32 v61, v61, v136
	v_mul_f32_e32 v62, v62, v136
	v_mul_f32_e32 v63, v63, v136
	v_mul_f32_e32 v56, v56, v136
	v_mul_f32_e32 v57, v57, v136
	v_mul_f32_e32 v58, v58, v136
	v_mul_f32_e32 v59, v59, v136
	v_mul_f32_e32 v60, 0xbfb8aa3b, v60
	v_mul_f32_e32 v61, 0xbfb8aa3b, v61
	v_mul_f32_e32 v62, 0xbfb8aa3b, v62
	v_mul_f32_e32 v63, 0xbfb8aa3b, v63
	v_mul_f32_e32 v56, 0xbfb8aa3b, v56
	v_mul_f32_e32 v57, 0xbfb8aa3b, v57
	v_mul_f32_e32 v58, 0xbfb8aa3b, v58
	v_mul_f32_e32 v59, 0xbfb8aa3b, v59
	v_exp_f32_e32 v60, v60
	v_exp_f32_e32 v61, v61
	v_exp_f32_e32 v62, v62
	v_exp_f32_e32 v63, v63
	v_exp_f32_e32 v56, v56
	v_exp_f32_e32 v57, v57
	v_exp_f32_e32 v58, v58
	v_exp_f32_e32 v59, v59
	v_add_f32_e32 v60, 1.0, v60
	v_add_f32_e32 v61, 1.0, v61
	v_add_f32_e32 v62, 1.0, v62
	v_add_f32_e32 v63, 1.0, v63
	v_add_f32_e32 v56, 1.0, v56
	v_add_f32_e32 v57, 1.0, v57
	v_add_f32_e32 v58, 1.0, v58
	v_add_f32_e32 v59, 1.0, v59
	v_rcp_f32_e32 v60, v60
	v_rcp_f32_e32 v61, v61
	v_rcp_f32_e32 v62, v62
	v_rcp_f32_e32 v63, v63
	v_rcp_f32_e32 v56, v56
	v_rcp_f32_e32 v57, v57
	v_rcp_f32_e32 v58, v58
	v_rcp_f32_e32 v59, v59
	v_cvt_pk_bf16_f32 v60, v60, v61
	v_cvt_pk_bf16_f32 v61, v62, v63
	v_cvt_pk_bf16_f32 v62, v56, v57
	v_cvt_pk_bf16_f32 v63, v58, v59
	global_store_dwordx4 v144, v[60:63], s[54:55]
	v_mul_f32_e32 v52, v52, v136
	v_mul_f32_e32 v53, v53, v136
	v_mul_f32_e32 v54, v54, v136
	v_mul_f32_e32 v55, v55, v136
	v_mul_f32_e32 v44, v44, v136
	v_mul_f32_e32 v45, v45, v136
	v_mul_f32_e32 v46, v46, v136
	v_mul_f32_e32 v47, v47, v136
	v_mul_f32_e32 v52, 0xbfb8aa3b, v52
	v_mul_f32_e32 v53, 0xbfb8aa3b, v53
	v_mul_f32_e32 v54, 0xbfb8aa3b, v54
	v_mul_f32_e32 v55, 0xbfb8aa3b, v55
	v_mul_f32_e32 v44, 0xbfb8aa3b, v44
	v_mul_f32_e32 v45, 0xbfb8aa3b, v45
	v_mul_f32_e32 v46, 0xbfb8aa3b, v46
	v_mul_f32_e32 v47, 0xbfb8aa3b, v47
	v_exp_f32_e32 v52, v52
	v_exp_f32_e32 v53, v53
	v_exp_f32_e32 v54, v54
	v_exp_f32_e32 v55, v55
	v_exp_f32_e32 v44, v44
	v_exp_f32_e32 v45, v45
	v_exp_f32_e32 v46, v46
	v_exp_f32_e32 v47, v47
	v_add_f32_e32 v52, 1.0, v52
	v_add_f32_e32 v53, 1.0, v53
	v_add_f32_e32 v54, 1.0, v54
	v_add_f32_e32 v55, 1.0, v55
	v_add_f32_e32 v44, 1.0, v44
	v_add_f32_e32 v45, 1.0, v45
	v_add_f32_e32 v46, 1.0, v46
	v_add_f32_e32 v47, 1.0, v47
	v_rcp_f32_e32 v52, v52
	v_rcp_f32_e32 v53, v53
	v_rcp_f32_e32 v54, v54
	v_rcp_f32_e32 v55, v55
	v_rcp_f32_e32 v44, v44
	v_rcp_f32_e32 v45, v45
	v_rcp_f32_e32 v46, v46
	v_rcp_f32_e32 v47, v47
	v_cvt_pk_bf16_f32 v52, v52, v53
	v_cvt_pk_bf16_f32 v53, v54, v55
	v_cvt_pk_bf16_f32 v54, v44, v45
	v_cvt_pk_bf16_f32 v55, v46, v47
	global_store_dwordx4 v144, v[52:55], s[54:55] offset:256
	v_mul_f32_e32 v48, v48, v137
	v_mul_f32_e32 v49, v49, v137
	v_mul_f32_e32 v50, v50, v137
	v_mul_f32_e32 v51, v51, v137
	v_mul_f32_e32 v40, v40, v137
	v_mul_f32_e32 v41, v41, v137
; __device__ __forceinline__ unsigned cvt_pk_bf16(float lo, float hi) { unsigned r; asm volatile("v_cvt_pk_bf16_f32 %0, %1, %2" : "=v"(r) : "v"(lo), "v"(hi)); return r; }
; __device__ __forceinline__ void run_epi(const GDesc& d, const f32x4 (&acc)[2][2][4][2], const Unit& u, int wr, int wc, int fr, int fq) {
;     ...
; #pragma unroll
;                 for (int bj = 0; bj < 2; ++bj) {
;                     const f32x4 v0 = acc[ai][bj][m][0], v1 = acc[ai][bj][m][1];
;                     float v[8] = {v0[0], v0[1], v0[2], v0[3], v1[0], v1[1], v1[2], v1[3]};
; #pragma unroll
;                     for (int i = 0; i < 8; ++i) { float x = v[i] * rs;
;                         if (d.act == 1) x = __builtin_amdgcn_rcpf(1.f + __builtin_amdgcn_exp2f(-1.4426950408889634f * x));
;                         else if (d.act == 2) { x = fmaxf(x, 0.f); x = x * x; }
;                         v[i] = x; }
;                     u32x4 w; w.x = cvt_pk_bf16(v[0], v[1]); w.y = cvt_pk_bf16(v[2], v[3]); w.z = cvt_pk_bf16(v[4], v[5]); w.w = cvt_pk_bf16(v[6], v[7]);
;                     *(u32x4*)(d.O + (size_t)row * d.ldc + col0 + bj * HALF) = w;
	v_mul_f32_e32 v42, v42, v137
	v_mul_f32_e32 v43, v43, v137
	v_mul_f32_e32 v48, 0xbfb8aa3b, v48
	v_mul_f32_e32 v49, 0xbfb8aa3b, v49
	v_mul_f32_e32 v50, 0xbfb8aa3b, v50
	v_mul_f32_e32 v51, 0xbfb8aa3b, v51
	v_mul_f32_e32 v40, 0xbfb8aa3b, v40
	v_mul_f32_e32 v41, 0xbfb8aa3b, v41
	v_mul_f32_e32 v42, 0xbfb8aa3b, v42
	v_mul_f32_e32 v43, 0xbfb8aa3b, v43
	v_exp_f32_e32 v48, v48
	v_exp_f32_e32 v49, v49
	v_exp_f32_e32 v50, v50
	v_exp_f32_e32 v51, v51
	v_exp_f32_e32 v40, v40
	v_exp_f32_e32 v41, v41
	v_exp_f32_e32 v42, v42
	v_exp_f32_e32 v43, v43
	v_add_f32_e32 v48, 1.0, v48
	v_add_f32_e32 v49, 1.0, v49
	v_add_f32_e32 v50, 1.0, v50
	v_add_f32_e32 v51, 1.0, v51
	v_add_f32_e32 v40, 1.0, v40
	v_add_f32_e32 v41, 1.0, v41
	v_add_f32_e32 v42, 1.0, v42
	v_add_f32_e32 v43, 1.0, v43
	v_rcp_f32_e32 v48, v48
	v_rcp_f32_e32 v49, v49
	v_rcp_f32_e32 v50, v50
	v_rcp_f32_e32 v51, v51
	v_rcp_f32_e32 v40, v40
	v_rcp_f32_e32 v41, v41
	v_rcp_f32_e32 v42, v42
	v_rcp_f32_e32 v43, v43
	v_cvt_pk_bf16_f32 v48, v48, v49
	v_cvt_pk_bf16_f32 v49, v50, v51
	v_cvt_pk_bf16_f32 v50, v40, v41
	v_cvt_pk_bf16_f32 v51, v42, v43
	global_store_dwordx4 v145, v[48:51], s[54:55]
	v_mul_f32_e32 v36, v36, v137
	v_mul_f32_e32 v37, v37, v137
	v_mul_f32_e32 v38, v38, v137
	v_mul_f32_e32 v39, v39, v137
	v_mul_f32_e32 v28, v28, v137
	v_mul_f32_e32 v29, v29, v137
	v_mul_f32_e32 v30, v30, v137
	v_mul_f32_e32 v31, v31, v137
	v_mul_f32_e32 v36, 0xbfb8aa3b, v36
	v_mul_f32_e32 v37, 0xbfb8aa3b, v37
	v_mul_f32_e32 v38, 0xbfb8aa3b, v38
	v_mul_f32_e32 v39, 0xbfb8aa3b, v39
	v_mul_f32_e32 v28, 0xbfb8aa3b, v28
	v_mul_f32_e32 v29, 0xbfb8aa3b, v29
	v_mul_f32_e32 v30, 0xbfb8aa3b, v30
	v_mul_f32_e32 v31, 0xbfb8aa3b, v31
	v_exp_f32_e32 v36, v36
	v_exp_f32_e32 v37, v37
	v_exp_f32_e32 v38, v38
	v_exp_f32_e32 v39, v39
	v_exp_f32_e32 v28, v28
	v_exp_f32_e32 v29, v29
	v_exp_f32_e32 v30, v30
	v_exp_f32_e32 v31, v31
	v_add_f32_e32 v36, 1.0, v36
	v_add_f32_e32 v37, 1.0, v37
	v_add_f32_e32 v38, 1.0, v38
	v_add_f32_e32 v39, 1.0, v39
	v_add_f32_e32 v28, 1.0, v28
	v_add_f32_e32 v29, 1.0, v29
	v_add_f32_e32 v30, 1.0, v30
	v_add_f32_e32 v31, 1.0, v31
	v_rcp_f32_e32 v36, v36
	v_rcp_f32_e32 v37, v37
	v_rcp_f32_e32 v38, v38
	v_rcp_f32_e32 v39, v39
	v_rcp_f32_e32 v28, v28
	v_rcp_f32_e32 v29, v29
	v_rcp_f32_e32 v30, v30
	v_rcp_f32_e32 v31, v31
	v_cvt_pk_bf16_f32 v36, v36, v37
	v_cvt_pk_bf16_f32 v37, v38, v39
	v_cvt_pk_bf16_f32 v38, v28, v29
	v_cvt_pk_bf16_f32 v39, v30, v31
	global_store_dwordx4 v145, v[36:39], s[54:55] offset:256
	v_mul_f32_e32 v32, v32, v138
	v_mul_f32_e32 v33, v33, v138
	v_mul_f32_e32 v34, v34, v138
	v_mul_f32_e32 v35, v35, v138
	v_mul_f32_e32 v24, v24, v138
	v_mul_f32_e32 v25, v25, v138
	v_mul_f32_e32 v26, v26, v138
	v_mul_f32_e32 v27, v27, v138
	v_mul_f32_e32 v32, 0xbfb8aa3b, v32
	v_mul_f32_e32 v33, 0xbfb8aa3b, v33
	v_mul_f32_e32 v34, 0xbfb8aa3b, v34
	v_mul_f32_e32 v35, 0xbfb8aa3b, v35
	v_mul_f32_e32 v24, 0xbfb8aa3b, v24
	v_mul_f32_e32 v25, 0xbfb8aa3b, v25
	v_mul_f32_e32 v26, 0xbfb8aa3b, v26
	v_mul_f32_e32 v27, 0xbfb8aa3b, v27
	v_exp_f32_e32 v32, v32
	v_exp_f32_e32 v33, v33
	v_exp_f32_e32 v34, v34
	v_exp_f32_e32 v35, v35
	v_exp_f32_e32 v24, v24
	v_exp_f32_e32 v25, v25
	v_exp_f32_e32 v26, v26
	v_exp_f32_e32 v27, v27
	v_add_f32_e32 v32, 1.0, v32
	v_add_f32_e32 v33, 1.0, v33
	v_add_f32_e32 v34, 1.0, v34
	v_add_f32_e32 v35, 1.0, v35
	v_add_f32_e32 v24, 1.0, v24
	v_add_f32_e32 v25, 1.0, v25
	v_add_f32_e32 v26, 1.0, v26
	v_add_f32_e32 v27, 1.0, v27
	v_rcp_f32_e32 v32, v32
	v_rcp_f32_e32 v33, v33
	v_rcp_f32_e32 v34, v34
	v_rcp_f32_e32 v35, v35
	v_rcp_f32_e32 v24, v24
	v_rcp_f32_e32 v25, v25
	v_rcp_f32_e32 v26, v26
	v_rcp_f32_e32 v27, v27
	v_cvt_pk_bf16_f32 v32, v32, v33
	v_cvt_pk_bf16_f32 v33, v34, v35
	v_cvt_pk_bf16_f32 v34, v24, v25
	v_cvt_pk_bf16_f32 v35, v26, v27
	global_store_dwordx4 v146, v[32:35], s[54:55]
	v_mul_f32_e32 v20, v20, v138
	v_mul_f32_e32 v21, v21, v138
	v_mul_f32_e32 v22, v22, v138
	v_mul_f32_e32 v23, v23, v138
	v_mul_f32_e32 v12, v12, v138
	v_mul_f32_e32 v13, v13, v138
	v_mul_f32_e32 v14, v14, v138
	v_mul_f32_e32 v15, v15, v138
	v_mul_f32_e32 v20, 0xbfb8aa3b, v20
	v_mul_f32_e32 v21, 0xbfb8aa3b, v21
	v_mul_f32_e32 v22, 0xbfb8aa3b, v22
	v_mul_f32_e32 v23, 0xbfb8aa3b, v23
	v_mul_f32_e32 v12, 0xbfb8aa3b, v12
	v_mul_f32_e32 v13, 0xbfb8aa3b, v13
	v_mul_f32_e32 v14, 0xbfb8aa3b, v14
	v_mul_f32_e32 v15, 0xbfb8aa3b, v15
	v_exp_f32_e32 v20, v20
	v_exp_f32_e32 v21, v21
	v_exp_f32_e32 v22, v22
	v_exp_f32_e32 v23, v23
	v_exp_f32_e32 v12, v12
	v_exp_f32_e32 v13, v13
	v_exp_f32_e32 v14, v14
	v_exp_f32_e32 v15, v15
	v_add_f32_e32 v20, 1.0, v20
	v_add_f32_e32 v21, 1.0, v21
	v_add_f32_e32 v22, 1.0, v22
	v_add_f32_e32 v23, 1.0, v23
	v_add_f32_e32 v12, 1.0, v12
	v_add_f32_e32 v13, 1.0, v13
	v_add_f32_e32 v14, 1.0, v14
	v_add_f32_e32 v15, 1.0, v15
	v_rcp_f32_e32 v20, v20
	v_rcp_f32_e32 v21, v21
	v_rcp_f32_e32 v22, v22
	v_rcp_f32_e32 v23, v23
	v_rcp_f32_e32 v12, v12
	v_rcp_f32_e32 v13, v13
	v_rcp_f32_e32 v14, v14
	v_rcp_f32_e32 v15, v15
	v_cvt_pk_bf16_f32 v20, v20, v21
	v_cvt_pk_bf16_f32 v21, v22, v23
	v_cvt_pk_bf16_f32 v22, v12, v13
	v_cvt_pk_bf16_f32 v23, v14, v15
	global_store_dwordx4 v146, v[20:23], s[54:55] offset:256
	v_mul_f32_e32 v16, v16, v139
	v_mul_f32_e32 v17, v17, v139
	v_mul_f32_e32 v18, v18, v139
	v_mul_f32_e32 v19, v19, v139
	v_mul_f32_e32 v8, v8, v139
	v_mul_f32_e32 v9, v9, v139
	v_mul_f32_e32 v10, v10, v139
	v_mul_f32_e32 v11, v11, v139
	v_mul_f32_e32 v16, 0xbfb8aa3b, v16
	v_mul_f32_e32 v17, 0xbfb8aa3b, v17
	v_mul_f32_e32 v18, 0xbfb8aa3b, v18
	v_mul_f32_e32 v19, 0xbfb8aa3b, v19
	v_mul_f32_e32 v8, 0xbfb8aa3b, v8
	v_mul_f32_e32 v9, 0xbfb8aa3b, v9
	v_mul_f32_e32 v10, 0xbfb8aa3b, v10
	v_mul_f32_e32 v11, 0xbfb8aa3b, v11
; __device__ __forceinline__ unsigned cvt_pk_bf16(float lo, float hi) { unsigned r; asm volatile("v_cvt_pk_bf16_f32 %0, %1, %2" : "=v"(r) : "v"(lo), "v"(hi)); return r; }
; __device__ __forceinline__ void run_epi(const GDesc& d, const f32x4 (&acc)[2][2][4][2], const Unit& u, int wr, int wc, int fr, int fq) {
;     ...
; #pragma unroll
;                 for (int bj = 0; bj < 2; ++bj) {
;                     const f32x4 v0 = acc[ai][bj][m][0], v1 = acc[ai][bj][m][1];
;                     float v[8] = {v0[0], v0[1], v0[2], v0[3], v1[0], v1[1], v1[2], v1[3]};
; #pragma unroll
;                     for (int i = 0; i < 8; ++i) { float x = v[i] * rs;
;                         if (d.act == 1) x = __builtin_amdgcn_rcpf(1.f + __builtin_amdgcn_exp2f(-1.4426950408889634f * x));
;                         else if (d.act == 2) { x = fmaxf(x, 0.f); x = x * x; }
;                         v[i] = x; }
;                     u32x4 w; w.x = cvt_pk_bf16(v[0], v[1]); w.y = cvt_pk_bf16(v[2], v[3]); w.z = cvt_pk_bf16(v[4], v[5]); w.w = cvt_pk_bf16(v[6], v[7]);
;                     *(u32x4*)(d.O + (size_t)row * d.ldc + col0 + bj * HALF) = w;
	v_exp_f32_e32 v16, v16
	v_exp_f32_e32 v17, v17
	v_exp_f32_e32 v18, v18
	v_exp_f32_e32 v19, v19
	v_exp_f32_e32 v8, v8
	v_exp_f32_e32 v9, v9
	v_exp_f32_e32 v10, v10
	v_exp_f32_e32 v11, v11
	v_add_f32_e32 v16, 1.0, v16
	v_add_f32_e32 v17, 1.0, v17
	v_add_f32_e32 v18, 1.0, v18
	v_add_f32_e32 v19, 1.0, v19
	v_add_f32_e32 v8, 1.0, v8
	v_add_f32_e32 v9, 1.0, v9
	v_add_f32_e32 v10, 1.0, v10
	v_add_f32_e32 v11, 1.0, v11
	v_rcp_f32_e32 v16, v16
	v_rcp_f32_e32 v17, v17
	v_rcp_f32_e32 v18, v18
	v_rcp_f32_e32 v19, v19
	v_rcp_f32_e32 v8, v8
	v_rcp_f32_e32 v9, v9
	v_rcp_f32_e32 v10, v10
	v_rcp_f32_e32 v11, v11
	v_cvt_pk_bf16_f32 v16, v16, v17
	v_cvt_pk_bf16_f32 v17, v18, v19
	v_cvt_pk_bf16_f32 v18, v8, v9
	v_cvt_pk_bf16_f32 v19, v10, v11
	global_store_dwordx4 v147, v[16:19], s[54:55]
	v_mul_f32_e32 v4, v4, v139
	v_mul_f32_e32 v5, v5, v139
	v_mul_f32_e32 v6, v6, v139
	v_mul_f32_e32 v7, v7, v139
	v_mul_f32_e32 v0, v0, v139
	v_mul_f32_e32 v1, v1, v139
	v_mul_f32_e32 v2, v2, v139
	v_mul_f32_e32 v3, v3, v139
	v_mul_f32_e32 v4, 0xbfb8aa3b, v4
	v_mul_f32_e32 v5, 0xbfb8aa3b, v5
	v_mul_f32_e32 v6, 0xbfb8aa3b, v6
	v_mul_f32_e32 v7, 0xbfb8aa3b, v7
	v_mul_f32_e32 v0, 0xbfb8aa3b, v0
	v_mul_f32_e32 v1, 0xbfb8aa3b, v1
	v_mul_f32_e32 v2, 0xbfb8aa3b, v2
	v_mul_f32_e32 v3, 0xbfb8aa3b, v3
	v_exp_f32_e32 v4, v4
	v_exp_f32_e32 v5, v5
	v_exp_f32_e32 v6, v6
	v_exp_f32_e32 v7, v7
	v_exp_f32_e32 v0, v0
	v_exp_f32_e32 v1, v1
	v_exp_f32_e32 v2, v2
	v_exp_f32_e32 v3, v3
	v_add_f32_e32 v4, 1.0, v4
	v_add_f32_e32 v5, 1.0, v5
	v_add_f32_e32 v6, 1.0, v6
	v_add_f32_e32 v7, 1.0, v7
	v_add_f32_e32 v0, 1.0, v0
	v_add_f32_e32 v1, 1.0, v1
	v_add_f32_e32 v2, 1.0, v2
	v_add_f32_e32 v3, 1.0, v3
	v_rcp_f32_e32 v4, v4
	v_rcp_f32_e32 v5, v5
	v_rcp_f32_e32 v6, v6
	v_rcp_f32_e32 v7, v7
	v_rcp_f32_e32 v0, v0
	v_rcp_f32_e32 v1, v1
	v_rcp_f32_e32 v2, v2
	v_rcp_f32_e32 v3, v3
	v_cvt_pk_bf16_f32 v4, v4, v5
	v_cvt_pk_bf16_f32 v5, v6, v7
	v_cvt_pk_bf16_f32 v6, v0, v1
	v_cvt_pk_bf16_f32 v7, v2, v3
	global_store_dwordx4 v147, v[4:7], s[54:55] offset:256
	s_branch .Le0_done
.Le0_relu2:
	v_mul_f32_e32 v124, v124, v132
	v_mul_f32_e32 v125, v125, v132
	v_mul_f32_e32 v126, v126, v132
	v_mul_f32_e32 v127, v127, v132
	v_mul_f32_e32 v120, v120, v132
	v_mul_f32_e32 v121, v121, v132
	v_mul_f32_e32 v122, v122, v132
	v_mul_f32_e32 v123, v123, v132
	v_max_f32_e32 v124, 0, v124
	v_max_f32_e32 v125, 0, v125
	v_max_f32_e32 v126, 0, v126
	v_max_f32_e32 v127, 0, v127
	v_max_f32_e32 v120, 0, v120
	v_max_f32_e32 v121, 0, v121
	v_max_f32_e32 v122, 0, v122
	v_max_f32_e32 v123, 0, v123
	v_mul_f32_e32 v124, v124, v124
	v_mul_f32_e32 v125, v125, v125
	v_mul_f32_e32 v126, v126, v126
	v_mul_f32_e32 v127, v127, v127
	v_mul_f32_e32 v120, v120, v120
	v_mul_f32_e32 v121, v121, v121
	v_mul_f32_e32 v122, v122, v122
	v_mul_f32_e32 v123, v123, v123
	v_cvt_pk_bf16_f32 v124, v124, v125
	v_cvt_pk_bf16_f32 v125, v126, v127
	v_cvt_pk_bf16_f32 v126, v120, v121
	v_cvt_pk_bf16_f32 v127, v122, v123
	global_store_dwordx4 v140, v[124:127], s[54:55]
	v_mul_f32_e32 v116, v116, v132
	v_mul_f32_e32 v117, v117, v132
	v_mul_f32_e32 v118, v118, v132
	v_mul_f32_e32 v119, v119, v132
	v_mul_f32_e32 v108, v108, v132
	v_mul_f32_e32 v109, v109, v132
	v_mul_f32_e32 v110, v110, v132
	v_mul_f32_e32 v111, v111, v132
	v_max_f32_e32 v116, 0, v116
	v_max_f32_e32 v117, 0, v117
	v_max_f32_e32 v118, 0, v118
	v_max_f32_e32 v119, 0, v119
	v_max_f32_e32 v108, 0, v108
	v_max_f32_e32 v109, 0, v109
	v_max_f32_e32 v110, 0, v110
	v_max_f32_e32 v111, 0, v111
	v_mul_f32_e32 v116, v116, v116
	v_mul_f32_e32 v117, v117, v117
	v_mul_f32_e32 v118, v118, v118
	v_mul_f32_e32 v119, v119, v119
	v_mul_f32_e32 v108, v108, v108
	v_mul_f32_e32 v109, v109, v109
	v_mul_f32_e32 v110, v110, v110
	v_mul_f32_e32 v111, v111, v111
	v_cvt_pk_bf16_f32 v116, v116, v117
	v_cvt_pk_bf16_f32 v117, v118, v119
	v_cvt_pk_bf16_f32 v118, v108, v109
	v_cvt_pk_bf16_f32 v119, v110, v111
	global_store_dwordx4 v140, v[116:119], s[54:55] offset:256
	v_mul_f32_e32 v112, v112, v133
	v_mul_f32_e32 v113, v113, v133
	v_mul_f32_e32 v114, v114, v133
	v_mul_f32_e32 v115, v115, v133
	v_mul_f32_e32 v104, v104, v133
	v_mul_f32_e32 v105, v105, v133
	v_mul_f32_e32 v106, v106, v133
	v_mul_f32_e32 v107, v107, v133
	v_max_f32_e32 v112, 0, v112
	v_max_f32_e32 v113, 0, v113
	v_max_f32_e32 v114, 0, v114
	v_max_f32_e32 v115, 0, v115
	v_max_f32_e32 v104, 0, v104
	v_max_f32_e32 v105, 0, v105
	v_max_f32_e32 v106, 0, v106
	v_max_f32_e32 v107, 0, v107
	v_mul_f32_e32 v112, v112, v112
	v_mul_f32_e32 v113, v113, v113
	v_mul_f32_e32 v114, v114, v114
	v_mul_f32_e32 v115, v115, v115
	v_mul_f32_e32 v104, v104, v104
	v_mul_f32_e32 v105, v105, v105
	v_mul_f32_e32 v106, v106, v106
	v_mul_f32_e32 v107, v107, v107
	v_cvt_pk_bf16_f32 v112, v112, v113
	v_cvt_pk_bf16_f32 v113, v114, v115
	v_cvt_pk_bf16_f32 v114, v104, v105
	v_cvt_pk_bf16_f32 v115, v106, v107
	global_store_dwordx4 v141, v[112:115], s[54:55]
	v_mul_f32_e32 v100, v100, v133
	v_mul_f32_e32 v101, v101, v133
	v_mul_f32_e32 v102, v102, v133
	v_mul_f32_e32 v103, v103, v133
	v_mul_f32_e32 v92, v92, v133
	v_mul_f32_e32 v93, v93, v133
	v_mul_f32_e32 v94, v94, v133
	v_mul_f32_e32 v95, v95, v133
	v_max_f32_e32 v100, 0, v100
	v_max_f32_e32 v101, 0, v101
	v_max_f32_e32 v102, 0, v102
	v_max_f32_e32 v103, 0, v103
	v_max_f32_e32 v92, 0, v92
	v_max_f32_e32 v93, 0, v93
	v_max_f32_e32 v94, 0, v94
	v_max_f32_e32 v95, 0, v95
	v_mul_f32_e32 v100, v100, v100
	v_mul_f32_e32 v101, v101, v101
	v_mul_f32_e32 v102, v102, v102
	v_mul_f32_e32 v103, v103, v103
	v_mul_f32_e32 v92, v92, v92
	v_mul_f32_e32 v93, v93, v93
	v_mul_f32_e32 v94, v94, v94
	v_mul_f32_e32 v95, v95, v95
	v_cvt_pk_bf16_f32 v100, v100, v101
; __device__ __forceinline__ unsigned cvt_pk_bf16(float lo, float hi) { unsigned r; asm volatile("v_cvt_pk_bf16_f32 %0, %1, %2" : "=v"(r) : "v"(lo), "v"(hi)); return r; }
; __device__ __forceinline__ void run_epi(const GDesc& d, const f32x4 (&acc)[2][2][4][2], const Unit& u, int wr, int wc, int fr, int fq) {
;     ...
; #pragma unroll
;                 for (int bj = 0; bj < 2; ++bj) {
;                     const f32x4 v0 = acc[ai][bj][m][0], v1 = acc[ai][bj][m][1];
;                     float v[8] = {v0[0], v0[1], v0[2], v0[3], v1[0], v1[1], v1[2], v1[3]};
; #pragma unroll
;                     for (int i = 0; i < 8; ++i) { float x = v[i] * rs;
;                         if (d.act == 1) x = __builtin_amdgcn_rcpf(1.f + __builtin_amdgcn_exp2f(-1.4426950408889634f * x));
;                         else if (d.act == 2) { x = fmaxf(x, 0.f); x = x * x; }
;                         v[i] = x; }
;                     u32x4 w; w.x = cvt_pk_bf16(v[0], v[1]); w.y = cvt_pk_bf16(v[2], v[3]); w.z = cvt_pk_bf16(v[4], v[5]); w.w = cvt_pk_bf16(v[6], v[7]);
;                     *(u32x4*)(d.O + (size_t)row * d.ldc + col0 + bj * HALF) = w;
	v_cvt_pk_bf16_f32 v101, v102, v103
	v_cvt_pk_bf16_f32 v102, v92, v93
	v_cvt_pk_bf16_f32 v103, v94, v95
	global_store_dwordx4 v141, v[100:103], s[54:55] offset:256
	v_mul_f32_e32 v96, v96, v134
	v_mul_f32_e32 v97, v97, v134
	v_mul_f32_e32 v98, v98, v134
	v_mul_f32_e32 v99, v99, v134
	v_mul_f32_e32 v88, v88, v134
	v_mul_f32_e32 v89, v89, v134
	v_mul_f32_e32 v90, v90, v134
	v_mul_f32_e32 v91, v91, v134
	v_max_f32_e32 v96, 0, v96
	v_max_f32_e32 v97, 0, v97
	v_max_f32_e32 v98, 0, v98
	v_max_f32_e32 v99, 0, v99
	v_max_f32_e32 v88, 0, v88
	v_max_f32_e32 v89, 0, v89
	v_max_f32_e32 v90, 0, v90
	v_max_f32_e32 v91, 0, v91
	v_mul_f32_e32 v96, v96, v96
	v_mul_f32_e32 v97, v97, v97
	v_mul_f32_e32 v98, v98, v98
	v_mul_f32_e32 v99, v99, v99
	v_mul_f32_e32 v88, v88, v88
	v_mul_f32_e32 v89, v89, v89
	v_mul_f32_e32 v90, v90, v90
	v_mul_f32_e32 v91, v91, v91
	v_cvt_pk_bf16_f32 v96, v96, v97
	v_cvt_pk_bf16_f32 v97, v98, v99
	v_cvt_pk_bf16_f32 v98, v88, v89
	v_cvt_pk_bf16_f32 v99, v90, v91
	global_store_dwordx4 v142, v[96:99], s[54:55]
	v_mul_f32_e32 v84, v84, v134
	v_mul_f32_e32 v85, v85, v134
	v_mul_f32_e32 v86, v86, v134
	v_mul_f32_e32 v87, v87, v134
	v_mul_f32_e32 v76, v76, v134
	v_mul_f32_e32 v77, v77, v134
	v_mul_f32_e32 v78, v78, v134
	v_mul_f32_e32 v79, v79, v134
	v_max_f32_e32 v84, 0, v84
	v_max_f32_e32 v85, 0, v85
	v_max_f32_e32 v86, 0, v86
	v_max_f32_e32 v87, 0, v87
	v_max_f32_e32 v76, 0, v76
	v_max_f32_e32 v77, 0, v77
	v_max_f32_e32 v78, 0, v78
	v_max_f32_e32 v79, 0, v79
	v_mul_f32_e32 v84, v84, v84
	v_mul_f32_e32 v85, v85, v85
	v_mul_f32_e32 v86, v86, v86
	v_mul_f32_e32 v87, v87, v87
	v_mul_f32_e32 v76, v76, v76
	v_mul_f32_e32 v77, v77, v77
	v_mul_f32_e32 v78, v78, v78
	v_mul_f32_e32 v79, v79, v79
	v_cvt_pk_bf16_f32 v84, v84, v85
	v_cvt_pk_bf16_f32 v85, v86, v87
	v_cvt_pk_bf16_f32 v86, v76, v77
	v_cvt_pk_bf16_f32 v87, v78, v79
	global_store_dwordx4 v142, v[84:87], s[54:55] offset:256
	v_mul_f32_e32 v80, v80, v135
	v_mul_f32_e32 v81, v81, v135
	v_mul_f32_e32 v82, v82, v135
	v_mul_f32_e32 v83, v83, v135
	v_mul_f32_e32 v72, v72, v135
	v_mul_f32_e32 v73, v73, v135
	v_mul_f32_e32 v74, v74, v135
	v_mul_f32_e32 v75, v75, v135
	v_max_f32_e32 v80, 0, v80
	v_max_f32_e32 v81, 0, v81
	v_max_f32_e32 v82, 0, v82
	v_max_f32_e32 v83, 0, v83
	v_max_f32_e32 v72, 0, v72
	v_max_f32_e32 v73, 0, v73
	v_max_f32_e32 v74, 0, v74
	v_max_f32_e32 v75, 0, v75
	v_mul_f32_e32 v80, v80, v80
	v_mul_f32_e32 v81, v81, v81
	v_mul_f32_e32 v82, v82, v82
	v_mul_f32_e32 v83, v83, v83
	v_mul_f32_e32 v72, v72, v72
	v_mul_f32_e32 v73, v73, v73
	v_mul_f32_e32 v74, v74, v74
	v_mul_f32_e32 v75, v75, v75
	v_cvt_pk_bf16_f32 v80, v80, v81
	v_cvt_pk_bf16_f32 v81, v82, v83
	v_cvt_pk_bf16_f32 v82, v72, v73
	v_cvt_pk_bf16_f32 v83, v74, v75
	global_store_dwordx4 v143, v[80:83], s[54:55]
	v_mul_f32_e32 v68, v68, v135
	v_mul_f32_e32 v69, v69, v135
	v_mul_f32_e32 v70, v70, v135
	v_mul_f32_e32 v71, v71, v135
	v_mul_f32_e32 v64, v64, v135
	v_mul_f32_e32 v65, v65, v135
	v_mul_f32_e32 v66, v66, v135
	v_mul_f32_e32 v67, v67, v135
	v_max_f32_e32 v68, 0, v68
	v_max_f32_e32 v69, 0, v69
	v_max_f32_e32 v70, 0, v70
	v_max_f32_e32 v71, 0, v71
	v_max_f32_e32 v64, 0, v64
	v_max_f32_e32 v65, 0, v65
	v_max_f32_e32 v66, 0, v66
	v_max_f32_e32 v67, 0, v67
	v_mul_f32_e32 v68, v68, v68
	v_mul_f32_e32 v69, v69, v69
	v_mul_f32_e32 v70, v70, v70
	v_mul_f32_e32 v71, v71, v71
	v_mul_f32_e32 v64, v64, v64
	v_mul_f32_e32 v65, v65, v65
	v_mul_f32_e32 v66, v66, v66
	v_mul_f32_e32 v67, v67, v67
	v_cvt_pk_bf16_f32 v68, v68, v69
	v_cvt_pk_bf16_f32 v69, v70, v71
	v_cvt_pk_bf16_f32 v70, v64, v65
	v_cvt_pk_bf16_f32 v71, v66, v67
	global_store_dwordx4 v143, v[68:71], s[54:55] offset:256
	v_mul_f32_e32 v60, v60, v136
	v_mul_f32_e32 v61, v61, v136
	v_mul_f32_e32 v62, v62, v136
	v_mul_f32_e32 v63, v63, v136
	v_mul_f32_e32 v56, v56, v136
	v_mul_f32_e32 v57, v57, v136
	v_mul_f32_e32 v58, v58, v136
	v_mul_f32_e32 v59, v59, v136
	v_max_f32_e32 v60, 0, v60
	v_max_f32_e32 v61, 0, v61
	v_max_f32_e32 v62, 0, v62
	v_max_f32_e32 v63, 0, v63
	v_max_f32_e32 v56, 0, v56
	v_max_f32_e32 v57, 0, v57
	v_max_f32_e32 v58, 0, v58
	v_max_f32_e32 v59, 0, v59
	v_mul_f32_e32 v60, v60, v60
	v_mul_f32_e32 v61, v61, v61
	v_mul_f32_e32 v62, v62, v62
	v_mul_f32_e32 v63, v63, v63
	v_mul_f32_e32 v56, v56, v56
	v_mul_f32_e32 v57, v57, v57
	v_mul_f32_e32 v58, v58, v58
	v_mul_f32_e32 v59, v59, v59
	v_cvt_pk_bf16_f32 v60, v60, v61
	v_cvt_pk_bf16_f32 v61, v62, v63
	v_cvt_pk_bf16_f32 v62, v56, v57
	v_cvt_pk_bf16_f32 v63, v58, v59
	global_store_dwordx4 v144, v[60:63], s[54:55]
	v_mul_f32_e32 v52, v52, v136
	v_mul_f32_e32 v53, v53, v136
	v_mul_f32_e32 v54, v54, v136
	v_mul_f32_e32 v55, v55, v136
	v_mul_f32_e32 v44, v44, v136
	v_mul_f32_e32 v45, v45, v136
	v_mul_f32_e32 v46, v46, v136
	v_mul_f32_e32 v47, v47, v136
	v_max_f32_e32 v52, 0, v52
	v_max_f32_e32 v53, 0, v53
	v_max_f32_e32 v54, 0, v54
	v_max_f32_e32 v55, 0, v55
	v_max_f32_e32 v44, 0, v44
	v_max_f32_e32 v45, 0, v45
	v_max_f32_e32 v46, 0, v46
	v_max_f32_e32 v47, 0, v47
	v_mul_f32_e32 v52, v52, v52
	v_mul_f32_e32 v53, v53, v53
	v_mul_f32_e32 v54, v54, v54
	v_mul_f32_e32 v55, v55, v55
	v_mul_f32_e32 v44, v44, v44
	v_mul_f32_e32 v45, v45, v45
	v_mul_f32_e32 v46, v46, v46
	v_mul_f32_e32 v47, v47, v47
	v_cvt_pk_bf16_f32 v52, v52, v53
	v_cvt_pk_bf16_f32 v53, v54, v55
	v_cvt_pk_bf16_f32 v54, v44, v45
	v_cvt_pk_bf16_f32 v55, v46, v47
	global_store_dwordx4 v144, v[52:55], s[54:55] offset:256
	v_mul_f32_e32 v48, v48, v137
	v_mul_f32_e32 v49, v49, v137
	v_mul_f32_e32 v50, v50, v137
	v_mul_f32_e32 v51, v51, v137
	v_mul_f32_e32 v40, v40, v137
	v_mul_f32_e32 v41, v41, v137
	v_mul_f32_e32 v42, v42, v137
	v_mul_f32_e32 v43, v43, v137
; __device__ __forceinline__ unsigned cvt_pk_bf16(float lo, float hi) { unsigned r; asm volatile("v_cvt_pk_bf16_f32 %0, %1, %2" : "=v"(r) : "v"(lo), "v"(hi)); return r; }
; __device__ __forceinline__ void run_epi(const GDesc& d, const f32x4 (&acc)[2][2][4][2], const Unit& u, int wr, int wc, int fr, int fq) {
;     ...
; #pragma unroll
;                 for (int bj = 0; bj < 2; ++bj) {
;                     const f32x4 v0 = acc[ai][bj][m][0], v1 = acc[ai][bj][m][1];
;                     float v[8] = {v0[0], v0[1], v0[2], v0[3], v1[0], v1[1], v1[2], v1[3]};
; #pragma unroll
;                     for (int i = 0; i < 8; ++i) { float x = v[i] * rs;
;                         if (d.act == 1) x = __builtin_amdgcn_rcpf(1.f + __builtin_amdgcn_exp2f(-1.4426950408889634f * x));
;                         else if (d.act == 2) { x = fmaxf(x, 0.f); x = x * x; }
;                         v[i] = x; }
;                     u32x4 w; w.x = cvt_pk_bf16(v[0], v[1]); w.y = cvt_pk_bf16(v[2], v[3]); w.z = cvt_pk_bf16(v[4], v[5]); w.w = cvt_pk_bf16(v[6], v[7]);
;                     *(u32x4*)(d.O + (size_t)row * d.ldc + col0 + bj * HALF) = w;
	v_max_f32_e32 v48, 0, v48
	v_max_f32_e32 v49, 0, v49
	v_max_f32_e32 v50, 0, v50
	v_max_f32_e32 v51, 0, v51
	v_max_f32_e32 v40, 0, v40
	v_max_f32_e32 v41, 0, v41
	v_max_f32_e32 v42, 0, v42
	v_max_f32_e32 v43, 0, v43
	v_mul_f32_e32 v48, v48, v48
	v_mul_f32_e32 v49, v49, v49
	v_mul_f32_e32 v50, v50, v50
	v_mul_f32_e32 v51, v51, v51
	v_mul_f32_e32 v40, v40, v40
	v_mul_f32_e32 v41, v41, v41
	v_mul_f32_e32 v42, v42, v42
	v_mul_f32_e32 v43, v43, v43
	v_cvt_pk_bf16_f32 v48, v48, v49
	v_cvt_pk_bf16_f32 v49, v50, v51
	v_cvt_pk_bf16_f32 v50, v40, v41
	v_cvt_pk_bf16_f32 v51, v42, v43
	global_store_dwordx4 v145, v[48:51], s[54:55]
	v_mul_f32_e32 v36, v36, v137
	v_mul_f32_e32 v37, v37, v137
	v_mul_f32_e32 v38, v38, v137
	v_mul_f32_e32 v39, v39, v137
	v_mul_f32_e32 v28, v28, v137
	v_mul_f32_e32 v29, v29, v137
	v_mul_f32_e32 v30, v30, v137
	v_mul_f32_e32 v31, v31, v137
	v_max_f32_e32 v36, 0, v36
	v_max_f32_e32 v37, 0, v37
	v_max_f32_e32 v38, 0, v38
	v_max_f32_e32 v39, 0, v39
	v_max_f32_e32 v28, 0, v28
	v_max_f32_e32 v29, 0, v29
	v_max_f32_e32 v30, 0, v30
	v_max_f32_e32 v31, 0, v31
	v_mul_f32_e32 v36, v36, v36
	v_mul_f32_e32 v37, v37, v37
	v_mul_f32_e32 v38, v38, v38
	v_mul_f32_e32 v39, v39, v39
	v_mul_f32_e32 v28, v28, v28
	v_mul_f32_e32 v29, v29, v29
	v_mul_f32_e32 v30, v30, v30
	v_mul_f32_e32 v31, v31, v31
	v_cvt_pk_bf16_f32 v36, v36, v37
	v_cvt_pk_bf16_f32 v37, v38, v39
	v_cvt_pk_bf16_f32 v38, v28, v29
	v_cvt_pk_bf16_f32 v39, v30, v31
	global_store_dwordx4 v145, v[36:39], s[54:55] offset:256
	v_mul_f32_e32 v32, v32, v138
	v_mul_f32_e32 v33, v33, v138
	v_mul_f32_e32 v34, v34, v138
	v_mul_f32_e32 v35, v35, v138
	v_mul_f32_e32 v24, v24, v138
	v_mul_f32_e32 v25, v25, v138
	v_mul_f32_e32 v26, v26, v138
	v_mul_f32_e32 v27, v27, v138
	v_max_f32_e32 v32, 0, v32
	v_max_f32_e32 v33, 0, v33
	v_max_f32_e32 v34, 0, v34
	v_max_f32_e32 v35, 0, v35
	v_max_f32_e32 v24, 0, v24
	v_max_f32_e32 v25, 0, v25
	v_max_f32_e32 v26, 0, v26
	v_max_f32_e32 v27, 0, v27
	v_mul_f32_e32 v32, v32, v32
	v_mul_f32_e32 v33, v33, v33
	v_mul_f32_e32 v34, v34, v34
	v_mul_f32_e32 v35, v35, v35
	v_mul_f32_e32 v24, v24, v24
	v_mul_f32_e32 v25, v25, v25
	v_mul_f32_e32 v26, v26, v26
	v_mul_f32_e32 v27, v27, v27
	v_cvt_pk_bf16_f32 v32, v32, v33
	v_cvt_pk_bf16_f32 v33, v34, v35
	v_cvt_pk_bf16_f32 v34, v24, v25
	v_cvt_pk_bf16_f32 v35, v26, v27
	global_store_dwordx4 v146, v[32:35], s[54:55]
	v_mul_f32_e32 v20, v20, v138
	v_mul_f32_e32 v21, v21, v138
	v_mul_f32_e32 v22, v22, v138
	v_mul_f32_e32 v23, v23, v138
	v_mul_f32_e32 v12, v12, v138
	v_mul_f32_e32 v13, v13, v138
	v_mul_f32_e32 v14, v14, v138
	v_mul_f32_e32 v15, v15, v138
	v_max_f32_e32 v20, 0, v20
	v_max_f32_e32 v21, 0, v21
	v_max_f32_e32 v22, 0, v22
	v_max_f32_e32 v23, 0, v23
	v_max_f32_e32 v12, 0, v12
	v_max_f32_e32 v13, 0, v13
	v_max_f32_e32 v14, 0, v14
	v_max_f32_e32 v15, 0, v15
	v_mul_f32_e32 v20, v20, v20
	v_mul_f32_e32 v21, v21, v21
	v_mul_f32_e32 v22, v22, v22
	v_mul_f32_e32 v23, v23, v23
	v_mul_f32_e32 v12, v12, v12
	v_mul_f32_e32 v13, v13, v13
	v_mul_f32_e32 v14, v14, v14
	v_mul_f32_e32 v15, v15, v15
	v_cvt_pk_bf16_f32 v20, v20, v21
	v_cvt_pk_bf16_f32 v21, v22, v23
	v_cvt_pk_bf16_f32 v22, v12, v13
	v_cvt_pk_bf16_f32 v23, v14, v15
	global_store_dwordx4 v146, v[20:23], s[54:55] offset:256
	v_mul_f32_e32 v16, v16, v139
	v_mul_f32_e32 v17, v17, v139
	v_mul_f32_e32 v18, v18, v139
	v_mul_f32_e32 v19, v19, v139
	v_mul_f32_e32 v8, v8, v139
	v_mul_f32_e32 v9, v9, v139
	v_mul_f32_e32 v10, v10, v139
	v_mul_f32_e32 v11, v11, v139
	v_max_f32_e32 v16, 0, v16
	v_max_f32_e32 v17, 0, v17
	v_max_f32_e32 v18, 0, v18
	v_max_f32_e32 v19, 0, v19
	v_max_f32_e32 v8, 0, v8
	v_max_f32_e32 v9, 0, v9
	v_max_f32_e32 v10, 0, v10
	v_max_f32_e32 v11, 0, v11
	v_mul_f32_e32 v16, v16, v16
	v_mul_f32_e32 v17, v17, v17
	v_mul_f32_e32 v18, v18, v18
	v_mul_f32_e32 v19, v19, v19
	v_mul_f32_e32 v8, v8, v8
	v_mul_f32_e32 v9, v9, v9
	v_mul_f32_e32 v10, v10, v10
	v_mul_f32_e32 v11, v11, v11
	v_cvt_pk_bf16_f32 v16, v16, v17
	v_cvt_pk_bf16_f32 v17, v18, v19
	v_cvt_pk_bf16_f32 v18, v8, v9
	v_cvt_pk_bf16_f32 v19, v10, v11
	global_store_dwordx4 v147, v[16:19], s[54:55]
	v_mul_f32_e32 v4, v4, v139
	v_mul_f32_e32 v5, v5, v139
	v_mul_f32_e32 v6, v6, v139
	v_mul_f32_e32 v7, v7, v139
	v_mul_f32_e32 v0, v0, v139
	v_mul_f32_e32 v1, v1, v139
	v_mul_f32_e32 v2, v2, v139
	v_mul_f32_e32 v3, v3, v139
	v_max_f32_e32 v4, 0, v4
	v_max_f32_e32 v5, 0, v5
	v_max_f32_e32 v6, 0, v6
	v_max_f32_e32 v7, 0, v7
	v_max_f32_e32 v0, 0, v0
	v_max_f32_e32 v1, 0, v1
	v_max_f32_e32 v2, 0, v2
	v_max_f32_e32 v3, 0, v3
	v_mul_f32_e32 v4, v4, v4
	v_mul_f32_e32 v5, v5, v5
	v_mul_f32_e32 v6, v6, v6
	v_mul_f32_e32 v7, v7, v7
	v_mul_f32_e32 v0, v0, v0
	v_mul_f32_e32 v1, v1, v1
	v_mul_f32_e32 v2, v2, v2
	v_mul_f32_e32 v3, v3, v3
	v_cvt_pk_bf16_f32 v4, v4, v5
	v_cvt_pk_bf16_f32 v5, v6, v7
	v_cvt_pk_bf16_f32 v6, v0, v1
	v_cvt_pk_bf16_f32 v7, v2, v3
	global_store_dwordx4 v147, v[4:7], s[54:55] offset:256
.Le0_done:
	s_mov_b64 s[0:1], 0
; __device__ __forceinline__ unsigned cvt_pk_bf16(float lo, float hi) { unsigned r; asm volatile("v_cvt_pk_bf16_f32 %0, %1, %2" : "=v"(r) : "v"(lo), "v"(hi)); return r; }
; __device__ __forceinline__ void run_epi(const GDesc& d, const f32x4 (&acc)[2][2][4][2], const Unit& u, int wr, int wc, int fr, int fq) {
;     ...
;     } else if (epi == 1) {
; #pragma unroll
;         for (int ai = 0; ai < 2; ++ai)
; #pragma unroll
;             for (int m = 0; m < 4; ++m) {
;                 const int row = row0 + ai * HALF + m * 16;
; #pragma unroll
;                 for (int bj = 0; bj < 2; ++bj) {
;                     const f32x4 v0 = acc[ai][bj][m][0], v1 = acc[ai][bj][m][1];
;                     u32x4 w; w.x = cvt_pk_bf16(v0[0], v0[1]); w.y = cvt_pk_bf16(v0[2], v0[3]); w.z = cvt_pk_bf16(v1[0], v1[1]); w.w = cvt_pk_bf16(v1[2], v1[3]);
;                     const int c = wc * 32 + 8 * fq;
;                     bf16_t* p = bj == 0 ? (bf16_t*)(d.ws + OFF_KF) + (size_t)row * 3072 + u.pn * 192 + c : (bf16_t*)(d.ws + OFF_V) + (size_t)row * 2048 + u.pn * 128 + c;
;                     *(u32x4*)p = w;
;                 }
;             }
.LBB0_1448:
	s_and_b64 vcc, exec, s[0:1]
	s_cbranch_vccz .LBB0_1450
	v_readlane_b32 s10, v246, 39
	s_mul_i32 s0, s96, 0xc0
	v_readlane_b32 s11, v246, 40
	s_ashr_i32 s1, s0, 31
	v_cvt_pk_bf16_f32 v124, v124, v125
	v_cvt_pk_bf16_f32 v125, v126, v127
	v_cvt_pk_bf16_f32 v126, v120, v121
	v_cvt_pk_bf16_f32 v127, v122, v123
	s_nop 0
	v_mov_b64_e32 v[120:121], s[10:11]
	v_mad_i64_i32 v[122:123], s[10:11], v208, s33, v[120:121]
	s_lshl_b64 s[0:1], s[0:1], 1
	s_lshl_b32 s8, s96, 7
	v_ashrrev_i32_e32 v209, 31, v208
	v_lshl_add_u64 v[122:123], v[122:123], 0, s[0:1]
	v_lshlrev_b32_e32 v196, 1, v206
	s_ashr_i32 s9, s8, 31
	s_waitcnt lgkmcnt(0)
	v_lshlrev_b64 v[130:131], 12, v[208:209]
	v_lshl_add_u64 v[122:123], v[122:123], 0, v[196:197]
	flat_store_dwordx4 v[122:123], v[124:127]
	v_cvt_pk_bf16_f32 v116, v116, v117
	v_cvt_pk_bf16_f32 v117, v118, v119
	v_cvt_pk_bf16_f32 v118, v108, v109
	v_lshl_add_u64 v[108:109], s[70:71], 0, v[130:131]
	s_lshl_b64 s[8:9], s[8:9], 1
	v_lshl_add_u64 v[108:109], v[108:109], 0, s[8:9]
	v_lshl_add_u64 v[108:109], v[108:109], 0, v[196:197]
	v_cvt_pk_bf16_f32 v119, v110, v111
	flat_store_dwordx4 v[108:109], v[116:119]
	v_cvt_pk_bf16_f32 v108, v112, v113
	v_cvt_pk_bf16_f32 v109, v114, v115
	v_cvt_pk_bf16_f32 v110, v104, v105
	v_cvt_pk_bf16_f32 v111, v106, v107
	s_nop 1
	v_or_b32_e32 v116, 16, v208
	v_mad_i64_i32 v[104:105], s[10:11], v116, s33, v[120:121]
	v_ashrrev_i32_e32 v117, 31, v116
	v_lshl_add_u64 v[104:105], v[104:105], 0, s[0:1]
	v_lshlrev_b64 v[118:119], 12, v[116:117]
	v_lshl_add_u64 v[104:105], v[104:105], 0, v[196:197]
	flat_store_dwordx4 v[104:105], v[108:111]
	v_cvt_pk_bf16_f32 v100, v100, v101
	v_cvt_pk_bf16_f32 v101, v102, v103
	v_cvt_pk_bf16_f32 v102, v92, v93
	v_lshl_add_u64 v[92:93], s[70:71], 0, v[118:119]
	v_lshl_add_u64 v[92:93], v[92:93], 0, s[8:9]
	v_lshl_add_u64 v[92:93], v[92:93], 0, v[196:197]
	v_cvt_pk_bf16_f32 v103, v94, v95
	flat_store_dwordx4 v[92:93], v[100:103]
	v_cvt_pk_bf16_f32 v92, v96, v97
	v_cvt_pk_bf16_f32 v93, v98, v99
	v_cvt_pk_bf16_f32 v94, v88, v89
	v_cvt_pk_bf16_f32 v95, v90, v91
	s_nop 1
	v_or_b32_e32 v100, 32, v208
	v_mad_i64_i32 v[88:89], s[10:11], v100, s33, v[120:121]
	v_ashrrev_i32_e32 v101, 31, v100
	v_lshl_add_u64 v[88:89], v[88:89], 0, s[0:1]
	v_lshlrev_b64 v[102:103], 12, v[100:101]
	v_lshl_add_u64 v[88:89], v[88:89], 0, v[196:197]
	flat_store_dwordx4 v[88:89], v[92:95]
	v_cvt_pk_bf16_f32 v84, v84, v85
	v_cvt_pk_bf16_f32 v85, v86, v87
	v_cvt_pk_bf16_f32 v86, v76, v77
	v_lshl_add_u64 v[76:77], s[70:71], 0, v[102:103]
	v_lshl_add_u64 v[76:77], v[76:77], 0, s[8:9]
	v_lshl_add_u64 v[76:77], v[76:77], 0, v[196:197]
	v_cvt_pk_bf16_f32 v87, v78, v79
	flat_store_dwordx4 v[76:77], v[84:87]
	v_cvt_pk_bf16_f32 v76, v80, v81
	v_cvt_pk_bf16_f32 v77, v82, v83
	v_cvt_pk_bf16_f32 v78, v72, v73
	v_cvt_pk_bf16_f32 v79, v74, v75
	s_nop 1
	v_or_b32_e32 v84, 48, v208
	v_mad_i64_i32 v[72:73], s[10:11], v84, s33, v[120:121]
	v_ashrrev_i32_e32 v85, 31, v84
	v_lshl_add_u64 v[72:73], v[72:73], 0, s[0:1]
	v_lshlrev_b64 v[86:87], 12, v[84:85]
	v_lshl_add_u64 v[72:73], v[72:73], 0, v[196:197]
	flat_store_dwordx4 v[72:73], v[76:79]
	v_cvt_pk_bf16_f32 v68, v68, v69
	v_cvt_pk_bf16_f32 v69, v70, v71
	v_cvt_pk_bf16_f32 v70, v64, v65
	v_lshl_add_u64 v[64:65], s[70:71], 0, v[86:87]
	v_lshl_add_u64 v[64:65], v[64:65], 0, s[8:9]
	v_lshl_add_u64 v[64:65], v[64:65], 0, v[196:197]
	v_cvt_pk_bf16_f32 v71, v66, v67
	flat_store_dwordx4 v[64:65], v[68:71]
	v_add_u32_e32 v64, 0x80, v208
	v_cvt_pk_bf16_f32 v60, v60, v61
	v_cvt_pk_bf16_f32 v61, v62, v63
	v_cvt_pk_bf16_f32 v62, v56, v57
	v_mad_i64_i32 v[56:57], s[10:11], v64, s33, v[120:121]
	v_ashrrev_i32_e32 v65, 31, v64
	v_lshl_add_u64 v[56:57], v[56:57], 0, s[0:1]
	v_lshlrev_b64 v[66:67], 12, v[64:65]
	v_lshl_add_u64 v[56:57], v[56:57], 0, v[196:197]
	v_cvt_pk_bf16_f32 v63, v58, v59
	flat_store_dwordx4 v[56:57], v[60:63]
	v_cvt_pk_bf16_f32 v52, v52, v53
	v_cvt_pk_bf16_f32 v53, v54, v55
	v_cvt_pk_bf16_f32 v54, v44, v45
	v_lshl_add_u64 v[44:45], s[70:71], 0, v[66:67]
	v_lshl_add_u64 v[44:45], v[44:45], 0, s[8:9]
	v_lshl_add_u64 v[44:45], v[44:45], 0, v[196:197]
	v_cvt_pk_bf16_f32 v55, v46, v47
	flat_store_dwordx4 v[44:45], v[52:55]
	v_cvt_pk_bf16_f32 v44, v48, v49
	v_cvt_pk_bf16_f32 v45, v50, v51
	v_cvt_pk_bf16_f32 v46, v40, v41
	v_cvt_pk_bf16_f32 v47, v42, v43
	s_nop 1
	v_add_u32_e32 v52, 0x90, v208
	v_mad_i64_i32 v[40:41], s[10:11], v52, s33, v[120:121]
	v_ashrrev_i32_e32 v53, 31, v52
	v_lshl_add_u64 v[40:41], v[40:41], 0, s[0:1]
	v_lshlrev_b64 v[54:55], 12, v[52:53]
	v_lshl_add_u64 v[40:41], v[40:41], 0, v[196:197]
	flat_store_dwordx4 v[40:41], v[44:47]
	v_cvt_pk_bf16_f32 v36, v36, v37
	v_cvt_pk_bf16_f32 v37, v38, v39
	v_cvt_pk_bf16_f32 v38, v28, v29
	v_lshl_add_u64 v[28:29], s[70:71], 0, v[54:55]
	v_lshl_add_u64 v[28:29], v[28:29], 0, s[8:9]
	v_lshl_add_u64 v[28:29], v[28:29], 0, v[196:197]
	v_cvt_pk_bf16_f32 v39, v30, v31
	flat_store_dwordx4 v[28:29], v[36:39]
	v_cvt_pk_bf16_f32 v28, v32, v33
	v_cvt_pk_bf16_f32 v29, v34, v35
	v_cvt_pk_bf16_f32 v30, v24, v25
	v_cvt_pk_bf16_f32 v31, v26, v27
	s_nop 1
	v_add_u32_e32 v36, 0xa0, v208
	v_mad_i64_i32 v[24:25], s[10:11], v36, s33, v[120:121]
	v_ashrrev_i32_e32 v37, 31, v36
	v_lshl_add_u64 v[24:25], v[24:25], 0, s[0:1]
	v_lshlrev_b64 v[38:39], 12, v[36:37]
	v_lshl_add_u64 v[24:25], v[24:25], 0, v[196:197]
	flat_store_dwordx4 v[24:25], v[28:31]
	v_cvt_pk_bf16_f32 v20, v20, v21
	v_cvt_pk_bf16_f32 v21, v22, v23
	v_cvt_pk_bf16_f32 v22, v12, v13
	v_lshl_add_u64 v[12:13], s[70:71], 0, v[38:39]
	v_lshl_add_u64 v[12:13], v[12:13], 0, s[8:9]
	v_lshl_add_u64 v[12:13], v[12:13], 0, v[196:197]
	v_cvt_pk_bf16_f32 v23, v14, v15
	flat_store_dwordx4 v[12:13], v[20:23]
	v_cvt_pk_bf16_f32 v12, v16, v17
	v_cvt_pk_bf16_f32 v13, v18, v19
	v_cvt_pk_bf16_f32 v14, v8, v9
	v_cvt_pk_bf16_f32 v15, v10, v11
	s_nop 1
	v_add_u32_e32 v20, 0xb0, v208
	v_mad_i64_i32 v[8:9], s[10:11], v20, s33, v[120:121]
	v_ashrrev_i32_e32 v21, 31, v20
	v_lshl_add_u64 v[8:9], v[8:9], 0, s[0:1]
	v_lshlrev_b64 v[22:23], 12, v[20:21]
	v_lshl_add_u64 v[8:9], v[8:9], 0, v[196:197]
	flat_store_dwordx4 v[8:9], v[12:15]
	v_cvt_pk_bf16_f32 v4, v4, v5
	v_cvt_pk_bf16_f32 v5, v6, v7
	v_cvt_pk_bf16_f32 v6, v0, v1
	v_lshl_add_u64 v[0:1], s[70:71], 0, v[22:23]
	v_lshl_add_u64 v[0:1], v[0:1], 0, s[8:9]
	v_lshl_add_u64 v[0:1], v[0:1], 0, v[196:197]
	v_cvt_pk_bf16_f32 v7, v2, v3
	flat_store_dwordx4 v[0:1], v[4:7]

; __device__ __forceinline__ int opaque_tid() { int t = threadIdx.x; asm volatile("" : "+v"(t)); return t; }
; #define VMW() asm volatile("s_waitcnt vmcnt(0)" ::: "memory")
; #define SLOAD(R_, k0) do { const size_t tr_ = (size_t)tokrow((R_).b, (k0) + srow); const bf16_t* kp_ = (const bf16_t*)(T.ws + OFF_KF) + tr_ * 3072 + (R_).h * 192 + c0 * 8; const bf16_t* vp_ = (const bf16_t*)(T.ws + OFF_V) + tr_ * 2048 + (R_).h * 128 + c0 * 8; \
;         S.st_v0 = ld8(vp_); S.st_v1 = ld8(vp_ + 64); S.st_k0 = ld8(kp_); S.st_k1 = ld8(kp_ + 64); S.st_k2 = ld8(kp_ + 128); } while (0)
; #define SWRITE_HK(bf) do { *(bf16x8*)(K_lds + (bf) * SHM_K + kws) = S.st_k0; *(bf16x8*)(K_lds + (bf) * SHM_K + kws + 128) = S.st_k1; *(bf16x8*)(K_lds + (bf) * SHM_K + kws + 256) = S.st_k2; } while (0)
; #define QLOAD(R_) do { const size_t qrow_ = (size_t)tokrow((R_).b, (R_).P0 + wid * QBLK + r32); const bf16_t* qp_ = (const bf16_t*)(T.ws + OFF_Q) + qrow_ * 3072 + (R_).h * 192 + hi * 8; \
;         _Pragma("unroll") for (int d0 = 0; d0 < 12; ++d0) S.qr[d0] = ld8(qp_ + d0 * 16); } while (0)
; __device__ __forceinline__ void attn_prime(const Ref& cur, const Tens& T, char* lds, Seam& S) {
;     const int tid = opaque_tid(), wid = __builtin_amdgcn_readfirstlane(tid >> 6), lane = tid & 63, r32 = lane & 31, hi = lane >> 5;
;     const int srow = tid >> 3, c0 = tid & 7, kws = KSWZ(srow, c0 * 16); char* K_lds = lds + 2 * SHM_V;
;     QLOAD(cur);
;     SLOAD(cur, 0); VMW(); SWRITE_HK(0);
;     __syncthreads();
; }
; __device__ __forceinline__ void attn_phase(char* lds, const Tens& T, int vcu, int G, bool nostore, bool with_meta) {
;     const int TOTAL = with_meta ? 512 + 16 : 512;
;     int L = vcu; if (L >= TOTAL) return;
;     int pass = 0;
;     Ref cur = make_ref(L, 0);
;     Seam S;
;     attn_prime(cur, T, lds, S);
.LBB0_1455:
	s_and_b64 vcc, exec, s[2:3]
	s_cbranch_vccz .LBB0_1612
	v_mov_b32_e32 v129, v194
	s_andn2_b64 vcc, exec, s[26:27]
	v_readfirstlane_b32 s16, v129
	s_cbranch_vccnz .LBB0_1611
	v_readlane_b32 s0, v246, 17
	s_cmp_lg_u32 s0, 5
	s_mov_b64 s[0:1], -1
	s_cbranch_scc0 .LBB0_1565
	v_writelane_b32 v246, s16, 19
	v_writelane_b32 v246, s26, 21
	s_nop 1
	v_writelane_b32 v246, s27, 22
	s_nop 0
	v_readlane_b32 s0, v246, 13
	v_readlane_b32 s1, v246, 14
	s_and_b64 s[0:1], s[0:1], exec
	s_movk_i32 s0, 0x210
	s_cselect_b32 s26, 0x200, s0
	v_readlane_b32 s0, v247, 36
	s_cmp_ge_i32 s0, s26
	s_cbranch_scc1 .LBB0_1564
	v_readfirstlane_b32 s0, v194
	s_nop 3
	s_cmpk_lt_u32 s0, 0x100
	s_cbranch_scc0 .La_prio_done
	s_setprio 2
.La_prio_done:
	s_waitcnt vmcnt(0)
	v_mov_b32_e32 v3, v194
	v_readlane_b32 s15, v247, 37
	v_readfirstlane_b32 s0, v3
	s_ashr_i32 s0, s0, 1
	s_andn2_b32 s0, s0, 31
	v_and_b32_e32 v0, 31, v3
	s_add_i32 s0, s0, s15
	v_add_u32_e32 v0, s0, v0
	v_min_u32_e32 v2, 0x100f, v0
	v_readlane_b32 s6, v247, 39
	s_add_u32 s2, s4, 0x17820000
	v_add_u32_e32 v1, 0x4000, v0
	v_add_u32_e32 v2, s6, v2
	v_cmp_gt_i32_e32 vcc, 16, v0
	s_addc_u32 s3, s5, 0
	v_readlane_b32 s8, v246, 11
	v_cndmask_b32_e32 v2, v2, v1, vcc
	v_mov_b64_e32 v[0:1], s[2:3]
	v_mad_i64_i32 v[0:1], s[0:1], v2, s33, v[0:1]
	v_readlane_b32 s9, v246, 12
	v_lshrrev_b32_e32 v2, 1, v3
	v_and_b32_e32 v196, 16, v2
	v_lshl_add_u64 v[0:1], v[0:1], 0, s[8:9]
	v_ashrrev_i32_e32 v6, 3, v3
	v_lshl_add_u64 v[0:1], v[0:1], 0, v[196:197]
	v_min_u32_e32 v4, 0x100f, v6
	s_add_u32 s0, s4, 0x1d9a0000
	flat_load_dwordx4 v[142:145], v[0:1]
	flat_load_dwordx4 v[138:141], v[0:1] offset:32
	flat_load_dwordx4 v[134:137], v[0:1] offset:64
	s_waitcnt lgkmcnt(0)
	flat_load_dwordx4 v[130:133], v[0:1] offset:96
	flat_load_dwordx4 v[116:119], v[0:1] offset:128
	flat_load_dwordx4 v[120:123], v[0:1] offset:160
	flat_load_dwordx4 v[124:127], v[0:1] offset:192
	flat_load_dwordx4 v[146:149], v[0:1] offset:224
	v_add_u32_e32 v2, 0x4000, v6
	v_add_u32_e32 v4, s6, v4
	v_cmp_gt_i32_e32 vcc, 16, v6
	s_addc_u32 s1, s5, 0
	v_writelane_b32 v246, s0, 23
	v_cndmask_b32_e32 v2, v4, v2, vcc
	v_lshlrev_b32_e32 v3, 4, v3
	v_mov_b64_e32 v[4:5], s[0:1]
	v_writelane_b32 v246, s1, 24
	v_mad_i64_i32 v[4:5], s[0:1], v2, s33, v[4:5]
	s_add_u32 s0, s4, 0x23b20000
	s_addc_u32 s1, s5, 0
	v_and_b32_e32 v196, 0x70, v3
	v_ashrrev_i32_e32 v3, 31, v2
	v_writelane_b32 v246, s0, 25
	v_lshlrev_b64 v[2:3], 12, v[2:3]
	v_lshl_add_u64 v[4:5], v[4:5], 0, s[8:9]
	v_writelane_b32 v246, s1, 26
	v_lshl_add_u64 v[2:3], s[0:1], 0, v[2:3]
	v_readlane_b32 s0, v246, 1
	v_readlane_b32 s1, v246, 2
	s_mov_b32 s1, s23
	v_lshl_add_u64 v[4:5], v[4:5], 0, v[196:197]
	v_lshl_add_u64 v[2:3], v[2:3], 0, s[0:1]
	v_lshl_add_u64 v[2:3], v[2:3], 0, v[196:197]
	flat_load_dwordx4 v[96:99], v[4:5]
	flat_load_dwordx4 v[100:103], v[4:5] offset:128
	flat_load_dwordx4 v[112:115], v[2:3]
	flat_load_dwordx4 v[108:111], v[4:5] offset:256
	flat_load_dwordx4 v[150:153], v[0:1] offset:256
	flat_load_dwordx4 v[154:157], v[0:1] offset:288
	flat_load_dwordx4 v[158:161], v[0:1] offset:320
	flat_load_dwordx4 v[162:165], v[0:1] offset:352
	flat_load_dwordx4 v[104:107], v[2:3] offset:128
	s_mov_b32 s4, s0
	v_writelane_b32 v246, s4, 1
	s_waitcnt vmcnt(0)
	v_readlane_b32 s28, v247, 52
	v_readlane_b32 s13, v247, 38
	v_writelane_b32 v246, s5, 2
	s_movk_i32 s4, 0x190
	v_mul_lo_u32 v0, v6, s4
	s_mov_b64 s[0:1], -1
	v_readlane_b32 s27, v247, 36
	s_mov_b32 s16, s15
	s_mov_b32 s12, s28
	v_add3_u32 v0, 0, v0, v196
	v_writelane_b32 v246, s13, 27
	v_writelane_b32 v246, s26, 29
	s_waitcnt vmcnt(0) lgkmcnt(0)
	ds_write_b128 v0, v[96:99] offset:32768
	ds_write_b128 v0, v[100:103] offset:32896
	ds_write_b128 v0, v[108:111] offset:33024
	s_waitcnt lgkmcnt(0)
	s_barrier
	s_branch .LBB0_1462

; __device__ __forceinline__ void attn_phase(char* lds, const Tens& T, int vcu, int G, bool nostore, bool with_meta) {
;     const int TOTAL = with_meta ? 512 + 16 : 512;
;     int L = vcu; if (L >= TOTAL) return;
;     int pass = 0;
;     Ref cur = make_ref(L, 0);
;     Seam S;
;     attn_prime(cur, T, lds, S);
;     for (;;) {
;         const bool more_pass = (pass == 0 && L < 512), more_item = L + G < TOTAL, last = !more_pass && !more_item;
;         int passn = pass + 1, Ln = L;
;         if (!more_pass) { passn = 0; Ln = more_item ? L + G : L; }
;         const Ref nxt = last ? cur : make_ref(Ln, passn);
;         attn_block(cur, nxt, T, lds, S, nostore);
;         if (last) break;
;         cur = nxt; pass = passn; L = Ln;
;     }
; }
.LBB0_1564:
	s_setprio 0
	v_readlane_b32 s26, v246, 21
	s_mov_b64 s[0:1], 0
	v_readlane_b32 s27, v246, 22
	v_readlane_b32 s16, v246, 19

; __global__ void __launch_bounds__(512, 2) fwd_megakernel(Params P) {
	.amdhsa_kernel _Z14fwd_megakernel6Params
		.amdhsa_group_segment_fixed_size 0
		.amdhsa_private_segment_fixed_size 0
		.amdhsa_kernarg_size 432
		.amdhsa_user_sgpr_count 2
		.amdhsa_user_sgpr_dispatch_ptr 0
		.amdhsa_user_sgpr_queue_ptr 0
		.amdhsa_user_sgpr_kernarg_segment_ptr 1
		.amdhsa_user_sgpr_dispatch_id 0
		.amdhsa_user_sgpr_kernarg_preload_length 0
		.amdhsa_user_sgpr_kernarg_preload_offset 0
		.amdhsa_user_sgpr_private_segment_size 0
		.amdhsa_uses_dynamic_stack 0
		.amdhsa_enable_private_segment 0
		.amdhsa_system_sgpr_workgroup_id_x 1
		.amdhsa_system_sgpr_workgroup_id_y 0
		.amdhsa_system_sgpr_workgroup_id_z 0
		.amdhsa_system_sgpr_workgroup_info 0
		.amdhsa_system_vgpr_workitem_id 2
		.amdhsa_next_free_vgpr 254
		.amdhsa_next_free_sgpr 98
		.amdhsa_accum_offset 256
		.amdhsa_reserve_vcc 1
		.amdhsa_float_round_mode_32 0
		.amdhsa_float_round_mode_16_64 0
		.amdhsa_float_denorm_mode_32 3
		.amdhsa_float_denorm_mode_16_64 3
		.amdhsa_dx10_clamp 1
		.amdhsa_ieee_mode 1
		.amdhsa_fp16_overflow 0
		.amdhsa_tg_split 0
		.amdhsa_exception_fp_ieee_invalid_op 0
		.amdhsa_exception_fp_denorm_src 0
		.amdhsa_exception_fp_ieee_div_zero 0
		.amdhsa_exception_fp_ieee_overflow 0
		.amdhsa_exception_fp_ieee_underflow 0
		.amdhsa_exception_fp_ieee_inexact 0
		.amdhsa_exception_int_div_zero 0
	.end_amdhsa_kernel

; __global__ void __launch_bounds__(512, 2) fwd_megakernel(Params P) {
;     extern __shared__ __attribute__((aligned(16))) unsigned char lds[];
amdhsa.kernels:
  - .agpr_count:     0
    .args:
      - .offset:         0
        .size:           176
        .value_kind:     by_value
      - .offset:         176
        .size:           4
        .value_kind:     hidden_block_count_x
      - .offset:         180
        .size:           4
        .value_kind:     hidden_block_count_y
      - .offset:         184
        .size:           4
        .value_kind:     hidden_block_count_z
      - .offset:         188
        .size:           2
        .value_kind:     hidden_group_size_x
      - .offset:         190
        .size:           2
        .value_kind:     hidden_group_size_y
      - .offset:         192
        .size:           2
        .value_kind:     hidden_group_size_z
      - .offset:         194
        .size:           2
        .value_kind:     hidden_remainder_x
      - .offset:         196
        .size:           2
        .value_kind:     hidden_remainder_y
      - .offset:         198
        .size:           2
        .value_kind:     hidden_remainder_z
      - .offset:         216
        .size:           8
        .value_kind:     hidden_global_offset_x
      - .offset:         224
        .size:           8
        .value_kind:     hidden_global_offset_y
      - .offset:         232
        .size:           8
        .value_kind:     hidden_global_offset_z
      - .offset:         240
        .size:           2
        .value_kind:     hidden_grid_dims
      - .offset:         264
        .size:           8
        .value_kind:     hidden_multigrid_sync_arg
      - .offset:         296
        .size:           4
        .value_kind:     hidden_dynamic_lds_size
    .group_segment_fixed_size: 0
    .kernarg_segment_align: 8
    .kernarg_segment_size: 432
    .language:       OpenCL C
    .language_version:
      - 2
      - 0
    .max_flat_workgroup_size: 512
    .name:           _Z14fwd_megakernel6Params
    .private_segment_fixed_size: 0
    .sgpr_count:     104
    .sgpr_spill_count: 267
    .symbol:         _Z14fwd_megakernel6Params.kd
    .uniform_work_group_size: 1
    .uses_dynamic_stack: false
    .vgpr_count:     254
    .vgpr_spill_count: 0
    .wavefront_size: 64
